# Swiglu epilogues: all 16 row-stat loads issued in one batch; IEEE 1/sqrtf chains -> v_rsq_f32 in Swiglu, EpiC, KVQ epilogues
# speedup vs baseline: 1.0048x; 1.0048x over previous
.LBB0_635:
	v_mov_b32_e32 v128, v172
	v_mov_b32_e32 v129, v173
	s_lshl_b32 s0, s0, 8
	s_add_i32 s0, s0, s36
	v_lshlrev_b32_e32 v144, 3, v129
	v_add_u32_e32 v181, s0, v128
	v_ashrrev_i32_e32 v145, 31, v144
	v_lshlrev_b32_e32 v160, 5, v181
	v_lshl_add_u64 v[182:183], v[144:145], 2, s[76:77]
	v_lshl_add_u64 v[132:133], v[160:161], 2, v[182:183]
	v_add_u32_e32 v136, 0x200, v160
	v_mov_b32_e32 v137, v161
	global_load_dwordx4 v[128:131], v[132:133], off
	s_nop 0
	global_load_dwordx4 v[132:135], v[132:133], off offset:16
	v_lshl_add_u64 v[140:141], v[136:137], 2, v[182:183]
	global_load_dwordx4 v[136:139], v[140:141], off
	s_nop 0
	global_load_dwordx4 v[140:143], v[140:141], off offset:16
	v_and_b32_e32 v148, 64, v178
	s_lshl_b32 s0, s1, 7
	v_xor_b32_e32 v146, 16, v178
	v_add_u32_e32 v148, 64, v148
	s_or_b32 s0, s0, s37
	v_cmp_lt_i32_e32 vcc, v146, v148
	v_mov_b32_e32 v145, v161
	v_add_u32_e32 v170, s0, v144
	v_cndmask_b32_e32 v146, v178, v146, vcc
	v_add_u32_e32 v144, 0x400, v160
	v_mov_b32_e32 v147, v161
	v_mov_b32_e32 v187, v161
	v_lshlrev_b32_e32 v171, 2, v146
	v_add_u32_e32 v146, 0x600, v160
	v_add_u32_e32 v186, 0x1400, v160
	v_lshl_add_u64 v[144:145], v[144:145], 2, v[182:183]
	v_lshl_add_u64 v[146:147], v[146:147], 2, v[182:183]
	v_lshl_add_u64 v[212:213], v[186:187], 2, v[182:183]
	global_load_dwordx4 v[186:189], v[144:145], off
	global_load_dwordx4 v[190:193], v[144:145], off offset:16
	global_load_dwordx4 v[194:197], v[146:147], off
	global_load_dwordx4 v[198:201], v[146:147], off offset:16
	v_xor_b32_e32 v150, 32, v178
	v_cmp_lt_i32_e32 vcc, v150, v148
	v_mov_b32_e32 v149, v161
	v_mov_b32_e32 v151, v161
	v_cndmask_b32_e32 v148, v178, v150, vcc
	v_lshlrev_b32_e32 v214, 2, v148
	v_add_u32_e32 v148, 0x1000, v160
	v_add_u32_e32 v150, 0x1200, v160
	v_add_u32_e32 v160, 0x1600, v160
	v_lshl_add_u64 v[148:149], v[148:149], 2, v[182:183]
	v_lshl_add_u64 v[210:211], v[150:151], 2, v[182:183]
	global_load_dwordx4 v[220:223], v[148:149], off
	global_load_dwordx4 v[224:227], v[148:149], off offset:16
	global_load_dwordx4 v[228:231], v[210:211], off
	global_load_dwordx4 v[232:235], v[210:211], off offset:16
	global_load_dwordx4 v[236:239], v[212:213], off
	global_load_dwordx4 v[240:243], v[212:213], off offset:16
	v_lshl_add_u64 v[252:253], v[160:161], 2, v[182:183]
	global_load_dwordx4 v[244:247], v[252:253], off
	global_load_dwordx4 v[248:251], v[252:253], off offset:16
	v_pk_mul_f32 v[122:123], v[126:127], v[122:123]
	v_pk_mul_f32 v[120:121], v[124:125], v[120:121]
	v_pk_mul_f32 v[112:113], v[116:117], v[112:113]
	v_pk_mul_f32 v[114:115], v[118:119], v[114:115]
	v_pk_mul_f32 v[106:107], v[110:111], v[106:107]
	v_pk_mul_f32 v[104:105], v[108:109], v[104:105]
	v_pk_mul_f32 v[98:99], v[102:103], v[98:99]
	v_pk_mul_f32 v[96:97], v[100:101], v[96:97]
	v_pk_mul_f32 v[90:91], v[94:95], v[90:91]
	v_pk_mul_f32 v[88:89], v[92:93], v[88:89]
	v_pk_mul_f32 v[82:83], v[86:87], v[82:83]
	v_pk_mul_f32 v[80:81], v[84:85], v[80:81]
	v_pk_mul_f32 v[74:75], v[78:79], v[74:75]
	v_pk_mul_f32 v[72:73], v[76:77], v[72:73]
	v_pk_mul_f32 v[66:67], v[70:71], v[66:67]
	v_pk_mul_f32 v[64:65], v[68:69], v[64:65]
	v_pk_mul_f32 v[58:59], v[62:63], v[58:59]
	v_pk_mul_f32 v[56:57], v[60:61], v[56:57]
	v_pk_mul_f32 v[50:51], v[54:55], v[50:51]
	v_pk_mul_f32 v[48:49], v[52:53], v[48:49]
	v_pk_mul_f32 v[42:43], v[46:47], v[42:43]
	v_pk_mul_f32 v[40:41], v[44:45], v[40:41]
	v_pk_mul_f32 v[34:35], v[38:39], v[34:35]
	v_pk_mul_f32 v[32:33], v[36:37], v[32:33]
	v_pk_mul_f32 v[26:27], v[30:31], v[26:27]
	v_pk_mul_f32 v[24:25], v[28:29], v[24:25]
	v_pk_mul_f32 v[18:19], v[22:23], v[18:19]
	v_pk_mul_f32 v[16:17], v[20:21], v[16:17]
	v_pk_mul_f32 v[10:11], v[14:15], v[10:11]
	v_pk_mul_f32 v[8:9], v[12:13], v[8:9]
	v_pk_mul_f32 v[2:3], v[6:7], v[2:3]
	v_pk_mul_f32 v[0:1], v[4:5], v[0:1]
	s_waitcnt vmcnt(0)
	v_mov_b32_e32 v144, v128
	v_mov_b32_e32 v145, v132
	v_mov_b32_e32 v132, v129
	v_mov_b32_e32 v128, v130
	v_mov_b32_e32 v129, v134
	v_mov_b32_e32 v134, v131
	v_mov_b32_e32 v130, v136
	v_mov_b32_e32 v131, v140
	v_mov_b32_e32 v140, v137
	v_mov_b32_e32 v136, v138
	v_mov_b32_e32 v137, v142
	v_mov_b32_e32 v142, v139
	v_pk_add_f32 v[132:133], v[144:145], v[132:133]
	v_pk_add_f32 v[128:129], v[128:129], v[134:135]
	v_pk_add_f32 v[130:131], v[130:131], v[140:141]
	v_pk_add_f32 v[134:135], v[136:137], v[142:143]
	v_pk_add_f32 v[128:129], v[132:133], v[128:129]
	v_pk_add_f32 v[130:131], v[130:131], v[134:135]
	v_add_f32_e32 v128, v128, v129
	v_add_f32_e32 v129, v130, v131
	ds_bpermute_b32 v130, v171, v128
	ds_bpermute_b32 v131, v171, v129
	s_nop 0
	s_waitcnt lgkmcnt(1)
	v_add_f32_e32 v130, v128, v130
	ds_bpermute_b32 v132, v214, v130
	s_waitcnt lgkmcnt(1)
	v_add_f32_e32 v131, v129, v131
	ds_bpermute_b32 v133, v214, v131
	s_waitcnt lgkmcnt(1)
	v_add_f32_e32 v130, v130, v132
	v_fmamk_f32 v130, v130, 0x3a000000, v179
	v_rsq_f32_e32 v202, v130
	s_waitcnt lgkmcnt(0)
	v_add_f32_e32 v131, v131, v133
	v_fmamk_f32 v131, v131, 0x3a000000, v179
	v_rsq_f32_e32 v203, v131
	v_mov_b32_e32 v182, v186
	v_mov_b32_e32 v183, v190
	v_mov_b32_e32 v190, v187
	v_mov_b32_e32 v186, v188
	v_mov_b32_e32 v187, v192
	v_mov_b32_e32 v192, v189
	v_pk_add_f32 v[182:183], v[182:183], v[190:191]
	v_pk_add_f32 v[186:187], v[186:187], v[192:193]
	v_pk_add_f32 v[182:183], v[182:183], v[186:187]
	v_add_f32_e32 v182, v182, v183
	ds_bpermute_b32 v183, v171, v182
	v_mov_b32_e32 v160, v202
	s_waitcnt lgkmcnt(0)
	v_add_f32_e32 v182, v182, v183
	ds_bpermute_b32 v183, v214, v182
	s_waitcnt lgkmcnt(0)
	v_add_f32_e32 v182, v182, v183
	v_fmamk_f32 v182, v182, 0x3a000000, v179
	v_rsq_f32_e32 v204, v182
	v_mov_b32_e32 v186, v196
	v_mov_b32_e32 v187, v200
	v_mov_b32_e32 v182, v194
	v_mov_b32_e32 v183, v198
	v_mov_b32_e32 v198, v195
	v_mov_b32_e32 v200, v197
	v_pk_add_f32 v[182:183], v[182:183], v[198:199]
	v_pk_add_f32 v[186:187], v[186:187], v[200:201]
	v_pk_add_f32 v[182:183], v[182:183], v[186:187]
	v_add_f32_e32 v182, v182, v183
	ds_bpermute_b32 v183, v171, v182
	v_mov_b32_e32 v188, v203
	s_waitcnt lgkmcnt(0)
	v_add_f32_e32 v182, v182, v183
	ds_bpermute_b32 v183, v214, v182
	s_waitcnt lgkmcnt(0)
	v_add_f32_e32 v182, v182, v183
	v_fmamk_f32 v182, v182, 0x3a000000, v179
	v_rsq_f32_e32 v205, v182
	s_waitcnt vmcnt(7)
	v_mov_b32_e32 v186, v222
	s_waitcnt vmcnt(6)
	v_mov_b32_e32 v187, v226
	v_mov_b32_e32 v182, v220
	v_mov_b32_e32 v183, v224
	v_mov_b32_e32 v224, v221
	v_mov_b32_e32 v226, v223
	v_pk_add_f32 v[182:183], v[182:183], v[224:225]
	v_pk_add_f32 v[186:187], v[186:187], v[226:227]
	v_pk_add_f32 v[182:183], v[182:183], v[186:187]
	v_add_f32_e32 v182, v182, v183
	ds_bpermute_b32 v183, v171, v182
	s_waitcnt lgkmcnt(0)
	v_add_f32_e32 v182, v182, v183
	ds_bpermute_b32 v183, v214, v182
	v_mov_b32_e32 v186, v204
	s_waitcnt lgkmcnt(0)
	v_add_f32_e32 v182, v182, v183
	v_fmamk_f32 v182, v182, 0x3a000000, v179
	v_rsq_f32_e32 v206, v182
	s_waitcnt vmcnt(5)
	v_mov_b32_e32 v182, v228
	s_waitcnt vmcnt(4)
	v_mov_b32_e32 v183, v232
	v_mov_b32_e32 v232, v229
	v_mov_b32_e32 v228, v230
	v_mov_b32_e32 v229, v234
	v_mov_b32_e32 v234, v231
	v_pk_add_f32 v[232:233], v[182:183], v[232:233]
	v_pk_add_f32 v[234:235], v[228:229], v[234:235]
	v_pk_add_f32 v[232:233], v[232:233], v[234:235]
	v_add_f32_e32 v232, v232, v233
	ds_bpermute_b32 v233, v171, v232
	s_waitcnt lgkmcnt(0)
	v_add_f32_e32 v232, v232, v233
	ds_bpermute_b32 v233, v214, v232
	s_waitcnt lgkmcnt(0)
	v_add_f32_e32 v232, v232, v233
	v_fmamk_f32 v232, v232, 0x3a000000, v179
	v_rsq_f32_e32 v207, v232
	v_mov_b32_e32 v234, v205
	s_waitcnt vmcnt(3)
	v_mov_b32_e32 v232, v236
	s_waitcnt vmcnt(2)
	v_mov_b32_e32 v233, v240
	v_mov_b32_e32 v240, v237
	v_mov_b32_e32 v236, v238
	v_mov_b32_e32 v237, v242
	v_mov_b32_e32 v242, v239
	v_pk_add_f32 v[240:241], v[232:233], v[240:241]
	v_pk_add_f32 v[242:243], v[236:237], v[242:243]
	v_pk_add_f32 v[240:241], v[240:241], v[242:243]
	v_add_f32_e32 v240, v240, v241
	ds_bpermute_b32 v241, v171, v240
	s_waitcnt lgkmcnt(0)
	v_add_f32_e32 v240, v240, v241
	ds_bpermute_b32 v241, v214, v240
	s_waitcnt lgkmcnt(0)
	v_add_f32_e32 v240, v240, v241
	v_fmamk_f32 v240, v240, 0x3a000000, v179
	v_rsq_f32_e32 v208, v240
	v_mov_b32_e32 v242, v206
	s_waitcnt vmcnt(1)
	v_mov_b32_e32 v240, v244
	s_waitcnt vmcnt(0)
	v_mov_b32_e32 v241, v248
	v_mov_b32_e32 v248, v245
	v_mov_b32_e32 v244, v246
	v_mov_b32_e32 v245, v250
	v_mov_b32_e32 v250, v247
	v_pk_add_f32 v[248:249], v[240:241], v[248:249]
	v_pk_add_f32 v[250:251], v[244:245], v[250:251]
	v_pk_add_f32 v[248:249], v[248:249], v[250:251]
	v_add_f32_e32 v248, v248, v249
	ds_bpermute_b32 v249, v171, v248
	v_mov_b32_e32 v251, v207
	s_waitcnt lgkmcnt(0)
	v_add_f32_e32 v248, v248, v249
	ds_bpermute_b32 v249, v214, v248
	s_waitcnt lgkmcnt(0)
	v_add_f32_e32 v248, v248, v249
	v_fmamk_f32 v248, v248, 0x3a000000, v179
	v_rsq_f32_e32 v209, v248
	v_mov_b32_e32 v243, v208
	v_ashrrev_i32_e32 v171, 31, v170
	v_mul_f32_e32 v250, 0xbfb8aa3b, v160
	v_pk_mul_f32 v[240:241], v[124:125], v[250:251] op_sel_hi:[1,0]
	v_mov_b32_e32 v248, v209
	v_exp_f32_e32 v249, v240
	v_pk_mul_f32 v[246:247], v[126:127], v[250:251] op_sel_hi:[1,0]
	v_exp_f32_e32 v245, v241
	v_exp_f32_e32 v240, v246
	v_exp_f32_e32 v241, v247
	v_add_f32_e32 v249, 1.0, v249
	v_rcp_f32_e32 v246, v249
	v_add_f32_e32 v249, 1.0, v245
	v_rcp_f32_e32 v247, v249
	v_add_f32_e32 v249, 1.0, v240
	v_pk_mul_f32 v[126:127], v[116:117], v[250:251] op_sel_hi:[1,0]
	v_rcp_f32_e32 v240, v249
	v_add_f32_e32 v249, 1.0, v241
	v_pk_mul_f32 v[124:125], v[118:119], v[250:251] op_sel_hi:[1,0]
	v_exp_f32_e32 v126, v126
	v_exp_f32_e32 v127, v127
	v_rcp_f32_e32 v241, v249
	v_exp_f32_e32 v249, v124
	v_exp_f32_e32 v250, v125
	v_add_f32_e32 v124, 1.0, v126
	v_add_f32_e32 v125, 1.0, v127
	v_rcp_f32_e32 v124, v124
	v_rcp_f32_e32 v125, v125
	v_add_f32_e32 v126, 1.0, v249
	v_add_f32_e32 v127, 1.0, v250
	v_rcp_f32_e32 v126, v126
	v_rcp_f32_e32 v127, v127
	v_mul_f32_e32 v244, v160, v160
	v_pk_mul_f32 v[112:113], v[112:113], v[244:245] op_sel_hi:[1,0]
	v_pk_mul_f32 v[120:121], v[120:121], v[244:245] op_sel_hi:[1,0]
	v_pk_mul_f32 v[122:123], v[122:123], v[244:245] op_sel_hi:[1,0]
	v_pk_mul_f32 v[114:115], v[114:115], v[244:245] op_sel_hi:[1,0]
	v_pk_mul_f32 v[112:113], v[112:113], v[124:125]
	v_pk_mul_f32 v[122:123], v[122:123], v[240:241]
	v_pk_mul_f32 v[120:121], v[120:121], v[246:247]
	v_pk_mul_f32 v[114:115], v[114:115], v[126:127]
	v_cvt_pk_bf16_f32 v116, v120, v121
	v_cvt_pk_bf16_f32 v117, v122, v123
	v_cvt_pk_bf16_f32 v118, v112, v113
	v_mov_b64_e32 v[112:113], s[68:69]
	v_cvt_pk_bf16_f32 v119, v114, v115
	v_mad_i64_i32 v[120:121], s[0:1], v181, s45, v[112:113]
	v_lshlrev_b64 v[114:115], 1, v[170:171]
	v_lshl_add_u64 v[120:121], v[120:121], 0, v[114:115]
	global_store_dwordx4 v[120:121], v[116:119], off
	s_andn2_b64 vcc, exec, s[4:5]
	s_nop 0
	v_mul_f32_e32 v116, 0xbfb8aa3b, v188
	v_pk_mul_f32 v[122:123], v[108:109], v[116:117] op_sel_hi:[1,0]
	v_pk_mul_f32 v[120:121], v[110:111], v[116:117] op_sel_hi:[1,0]
	v_exp_f32_e32 v117, v122
	v_exp_f32_e32 v119, v123
	v_exp_f32_e32 v122, v120
	v_exp_f32_e32 v123, v121
	v_add_f32_e32 v117, 1.0, v117
	v_rcp_f32_e32 v120, v117
	v_add_f32_e32 v117, 1.0, v119
	v_rcp_f32_e32 v121, v117
	v_add_f32_e32 v117, 1.0, v122
	v_rcp_f32_e32 v122, v117
	v_add_f32_e32 v117, 1.0, v123
	v_pk_mul_f32 v[108:109], v[102:103], v[116:117] op_sel_hi:[1,0]
	v_pk_mul_f32 v[110:111], v[100:101], v[116:117] op_sel_hi:[1,0]
	v_rcp_f32_e32 v123, v117
	v_exp_f32_e32 v110, v110
	v_exp_f32_e32 v111, v111
	v_exp_f32_e32 v116, v108
	v_exp_f32_e32 v117, v109
	v_add_f32_e32 v108, 1.0, v110
	v_add_f32_e32 v109, 1.0, v111
	v_add_f32_e32 v110, 1.0, v116
	v_add_f32_e32 v111, 1.0, v117
	v_rcp_f32_e32 v108, v108
	v_rcp_f32_e32 v109, v109
	v_rcp_f32_e32 v110, v110
	v_rcp_f32_e32 v111, v111
	v_mul_f32_e32 v118, v188, v188
	v_pk_mul_f32 v[96:97], v[96:97], v[118:119] op_sel_hi:[1,0]
	v_pk_mul_f32 v[98:99], v[98:99], v[118:119] op_sel_hi:[1,0]
	v_pk_mul_f32 v[104:105], v[104:105], v[118:119] op_sel_hi:[1,0]
	v_pk_mul_f32 v[106:107], v[106:107], v[118:119] op_sel_hi:[1,0]
	v_pk_mul_f32 v[100:101], v[98:99], v[110:111]
	v_pk_mul_f32 v[98:99], v[96:97], v[108:109]
	v_add_u32_e32 v102, 16, v181
	v_pk_mul_f32 v[106:107], v[106:107], v[122:123]
	v_pk_mul_f32 v[104:105], v[104:105], v[120:121]
	s_nop 0
	v_cvt_pk_bf16_f32 v96, v104, v105
	v_cvt_pk_bf16_f32 v97, v106, v107
	v_cvt_pk_bf16_f32 v98, v98, v99
	v_cvt_pk_bf16_f32 v99, v100, v101
	v_mad_i64_i32 v[100:101], s[0:1], v102, s45, v[112:113]
	v_lshl_add_u64 v[100:101], v[100:101], 0, v[114:115]
	global_store_dwordx4 v[100:101], v[96:99], off
	s_nop 1
	v_mul_f32_e32 v96, 0xbfb8aa3b, v186
	v_pk_mul_f32 v[102:103], v[92:93], v[96:97] op_sel_hi:[1,0]
	v_pk_mul_f32 v[100:101], v[94:95], v[96:97] op_sel_hi:[1,0]
	v_exp_f32_e32 v97, v102
	v_exp_f32_e32 v99, v103
	v_exp_f32_e32 v102, v100
	v_exp_f32_e32 v103, v101
	v_add_f32_e32 v97, 1.0, v97
	v_rcp_f32_e32 v100, v97
	v_add_f32_e32 v97, 1.0, v99
	v_rcp_f32_e32 v101, v97
	v_add_f32_e32 v97, 1.0, v102
	v_rcp_f32_e32 v102, v97
	v_add_f32_e32 v97, 1.0, v103
	v_pk_mul_f32 v[92:93], v[86:87], v[96:97] op_sel_hi:[1,0]
	v_pk_mul_f32 v[94:95], v[84:85], v[96:97] op_sel_hi:[1,0]
	v_rcp_f32_e32 v103, v97
	v_exp_f32_e32 v94, v94
	v_exp_f32_e32 v95, v95
	v_exp_f32_e32 v96, v92
	v_exp_f32_e32 v97, v93
	v_add_f32_e32 v92, 1.0, v94
	v_add_f32_e32 v93, 1.0, v95
	v_add_f32_e32 v94, 1.0, v96
	v_add_f32_e32 v95, 1.0, v97
	v_rcp_f32_e32 v92, v92
	v_rcp_f32_e32 v93, v93
	v_rcp_f32_e32 v94, v94
	v_rcp_f32_e32 v95, v95
	v_mul_f32_e32 v98, v186, v186
	v_pk_mul_f32 v[80:81], v[80:81], v[98:99] op_sel_hi:[1,0]
	v_pk_mul_f32 v[82:83], v[82:83], v[98:99] op_sel_hi:[1,0]
	v_pk_mul_f32 v[88:89], v[88:89], v[98:99] op_sel_hi:[1,0]
	v_pk_mul_f32 v[90:91], v[90:91], v[98:99] op_sel_hi:[1,0]
	v_pk_mul_f32 v[84:85], v[82:83], v[94:95]
	v_pk_mul_f32 v[82:83], v[80:81], v[92:93]
	v_add_u32_e32 v86, 32, v181
	v_pk_mul_f32 v[90:91], v[90:91], v[102:103]
	v_pk_mul_f32 v[88:89], v[88:89], v[100:101]
	s_nop 0
	v_cvt_pk_bf16_f32 v80, v88, v89
	v_cvt_pk_bf16_f32 v81, v90, v91
	v_cvt_pk_bf16_f32 v82, v82, v83
	v_cvt_pk_bf16_f32 v83, v84, v85
	v_mad_i64_i32 v[84:85], s[0:1], v86, s45, v[112:113]
	v_lshl_add_u64 v[84:85], v[84:85], 0, v[114:115]
	global_store_dwordx4 v[84:85], v[80:83], off
	s_nop 1
	v_mul_f32_e32 v80, 0xbfb8aa3b, v234
	v_pk_mul_f32 v[86:87], v[76:77], v[80:81] op_sel_hi:[1,0]
	v_pk_mul_f32 v[84:85], v[78:79], v[80:81] op_sel_hi:[1,0]
	v_exp_f32_e32 v81, v86
	v_exp_f32_e32 v83, v87
	v_exp_f32_e32 v86, v84
	v_exp_f32_e32 v87, v85
	v_add_f32_e32 v81, 1.0, v81
	v_rcp_f32_e32 v84, v81
	v_add_f32_e32 v81, 1.0, v83
	v_rcp_f32_e32 v85, v81
	v_add_f32_e32 v81, 1.0, v86
	v_rcp_f32_e32 v86, v81
	v_add_f32_e32 v81, 1.0, v87
	v_pk_mul_f32 v[76:77], v[70:71], v[80:81] op_sel_hi:[1,0]
	v_pk_mul_f32 v[78:79], v[68:69], v[80:81] op_sel_hi:[1,0]
	v_rcp_f32_e32 v87, v81
	v_exp_f32_e32 v78, v78
	v_exp_f32_e32 v79, v79
	v_exp_f32_e32 v80, v76
	v_exp_f32_e32 v81, v77
	v_add_f32_e32 v76, 1.0, v78
	v_add_f32_e32 v77, 1.0, v79
	v_add_f32_e32 v78, 1.0, v80
	v_add_f32_e32 v79, 1.0, v81
	v_rcp_f32_e32 v76, v76
	v_rcp_f32_e32 v77, v77
	v_rcp_f32_e32 v78, v78
	v_rcp_f32_e32 v79, v79
	v_mul_f32_e32 v82, v234, v234
	v_pk_mul_f32 v[64:65], v[64:65], v[82:83] op_sel_hi:[1,0]
	v_pk_mul_f32 v[66:67], v[66:67], v[82:83] op_sel_hi:[1,0]
	v_pk_mul_f32 v[72:73], v[72:73], v[82:83] op_sel_hi:[1,0]
	v_pk_mul_f32 v[74:75], v[74:75], v[82:83] op_sel_hi:[1,0]
	v_pk_mul_f32 v[68:69], v[66:67], v[78:79]
	v_pk_mul_f32 v[66:67], v[64:65], v[76:77]
	v_add_u32_e32 v70, 48, v181
	v_pk_mul_f32 v[74:75], v[74:75], v[86:87]
	v_pk_mul_f32 v[72:73], v[72:73], v[84:85]
	s_nop 0
	v_cvt_pk_bf16_f32 v64, v72, v73
	v_cvt_pk_bf16_f32 v65, v74, v75
	v_cvt_pk_bf16_f32 v66, v66, v67
	v_cvt_pk_bf16_f32 v67, v68, v69
	v_mad_i64_i32 v[68:69], s[0:1], v70, s45, v[112:113]
	v_lshl_add_u64 v[68:69], v[68:69], 0, v[114:115]
	global_store_dwordx4 v[68:69], v[64:67], off
	s_nop 1
	v_add_u32_e32 v65, 0x80, v181
	v_mul_f32_e32 v64, 0xbfb8aa3b, v242
	v_pk_mul_f32 v[70:71], v[60:61], v[64:65] op_sel_hi:[1,0]
	v_pk_mul_f32 v[68:69], v[62:63], v[64:65] op_sel_hi:[1,0]
	v_exp_f32_e32 v67, v70
	v_exp_f32_e32 v70, v71
	v_exp_f32_e32 v71, v68
	v_exp_f32_e32 v72, v69
	v_add_f32_e32 v67, 1.0, v67
	v_rcp_f32_e32 v68, v67
	v_add_f32_e32 v67, 1.0, v70
	v_rcp_f32_e32 v69, v67
	v_add_f32_e32 v67, 1.0, v71
	v_mul_f32_e32 v66, v242, v242
	v_rcp_f32_e32 v70, v67
	v_add_f32_e32 v67, 1.0, v72
	v_pk_mul_f32 v[60:61], v[54:55], v[64:65] op_sel_hi:[1,0]
	v_pk_mul_f32 v[62:63], v[52:53], v[64:65] op_sel_hi:[1,0]
	v_rcp_f32_e32 v71, v67
	v_pk_mul_f32 v[56:57], v[56:57], v[66:67] op_sel_hi:[1,0]
	v_pk_mul_f32 v[58:59], v[58:59], v[66:67] op_sel_hi:[1,0]
	v_exp_f32_e32 v62, v62
	v_exp_f32_e32 v63, v63
	v_exp_f32_e32 v64, v60
	v_exp_f32_e32 v67, v61
	v_add_f32_e32 v60, 1.0, v62
	v_add_f32_e32 v61, 1.0, v63
	v_add_f32_e32 v62, 1.0, v64
	v_add_f32_e32 v63, 1.0, v67
	v_rcp_f32_e32 v60, v60
	v_rcp_f32_e32 v61, v61
	v_rcp_f32_e32 v62, v62
	v_rcp_f32_e32 v63, v63
	v_pk_mul_f32 v[48:49], v[48:49], v[66:67] op_sel_hi:[1,0]
	v_pk_mul_f32 v[50:51], v[50:51], v[66:67] op_sel_hi:[1,0]
	v_pk_mul_f32 v[58:59], v[58:59], v[70:71]
	v_pk_mul_f32 v[52:53], v[50:51], v[62:63]
	v_pk_mul_f32 v[50:51], v[48:49], v[60:61]
	v_pk_mul_f32 v[56:57], v[56:57], v[68:69]
	s_nop 0
	v_cvt_pk_bf16_f32 v48, v56, v57
	v_cvt_pk_bf16_f32 v49, v58, v59
	v_cvt_pk_bf16_f32 v50, v50, v51
	v_cvt_pk_bf16_f32 v51, v52, v53
	v_mad_i64_i32 v[52:53], s[0:1], v65, s45, v[112:113]
	v_lshl_add_u64 v[52:53], v[52:53], 0, v[114:115]
	global_store_dwordx4 v[52:53], v[48:51], off
	s_nop 1
	v_mul_f32_e32 v48, 0xbfb8aa3b, v251
	v_pk_mul_f32 v[54:55], v[44:45], v[48:49] op_sel_hi:[1,0]
	v_pk_mul_f32 v[52:53], v[46:47], v[48:49] op_sel_hi:[1,0]
	v_exp_f32_e32 v49, v54
	v_exp_f32_e32 v51, v55
	v_exp_f32_e32 v54, v52
	v_exp_f32_e32 v55, v53
	v_add_f32_e32 v49, 1.0, v49
	v_rcp_f32_e32 v52, v49
	v_add_f32_e32 v49, 1.0, v51
	v_rcp_f32_e32 v53, v49
	v_add_f32_e32 v49, 1.0, v54
	v_rcp_f32_e32 v54, v49
	v_add_f32_e32 v49, 1.0, v55
	v_pk_mul_f32 v[44:45], v[38:39], v[48:49] op_sel_hi:[1,0]
	v_pk_mul_f32 v[46:47], v[36:37], v[48:49] op_sel_hi:[1,0]
	v_rcp_f32_e32 v55, v49
	v_exp_f32_e32 v46, v46
	v_exp_f32_e32 v47, v47
	v_exp_f32_e32 v48, v44
	v_exp_f32_e32 v49, v45
	v_add_f32_e32 v44, 1.0, v46
	v_add_f32_e32 v45, 1.0, v47
	v_add_f32_e32 v46, 1.0, v48
	v_add_f32_e32 v47, 1.0, v49
	v_rcp_f32_e32 v44, v44
	v_rcp_f32_e32 v45, v45
	v_rcp_f32_e32 v46, v46
	v_rcp_f32_e32 v47, v47
	v_mul_f32_e32 v50, v251, v251
	v_pk_mul_f32 v[32:33], v[32:33], v[50:51] op_sel_hi:[1,0]
	v_pk_mul_f32 v[34:35], v[34:35], v[50:51] op_sel_hi:[1,0]
	v_pk_mul_f32 v[40:41], v[40:41], v[50:51] op_sel_hi:[1,0]
	v_pk_mul_f32 v[42:43], v[42:43], v[50:51] op_sel_hi:[1,0]
	v_pk_mul_f32 v[36:37], v[34:35], v[46:47]
	v_pk_mul_f32 v[34:35], v[32:33], v[44:45]
	v_add_u32_e32 v38, 0x90, v181
	v_pk_mul_f32 v[42:43], v[42:43], v[54:55]
	v_pk_mul_f32 v[40:41], v[40:41], v[52:53]
	s_nop 0
	v_cvt_pk_bf16_f32 v32, v40, v41
	v_cvt_pk_bf16_f32 v33, v42, v43
	v_cvt_pk_bf16_f32 v34, v34, v35
	v_cvt_pk_bf16_f32 v35, v36, v37
	v_mad_i64_i32 v[36:37], s[0:1], v38, s45, v[112:113]
	v_lshl_add_u64 v[36:37], v[36:37], 0, v[114:115]
	global_store_dwordx4 v[36:37], v[32:35], off
	s_nop 1
	v_mul_f32_e32 v32, 0xbfb8aa3b, v243
	v_pk_mul_f32 v[38:39], v[28:29], v[32:33] op_sel_hi:[1,0]
	v_pk_mul_f32 v[36:37], v[30:31], v[32:33] op_sel_hi:[1,0]
	v_exp_f32_e32 v33, v38
	v_exp_f32_e32 v35, v39
	v_exp_f32_e32 v38, v36
	v_exp_f32_e32 v39, v37
	v_add_f32_e32 v33, 1.0, v33
	v_rcp_f32_e32 v36, v33
	v_add_f32_e32 v33, 1.0, v35
	v_rcp_f32_e32 v37, v33
	v_add_f32_e32 v33, 1.0, v38
	v_rcp_f32_e32 v38, v33
	v_add_f32_e32 v33, 1.0, v39
	v_pk_mul_f32 v[28:29], v[22:23], v[32:33] op_sel_hi:[1,0]
	v_pk_mul_f32 v[30:31], v[20:21], v[32:33] op_sel_hi:[1,0]
	v_rcp_f32_e32 v39, v33
	v_exp_f32_e32 v30, v30
	v_exp_f32_e32 v31, v31
	v_exp_f32_e32 v32, v28
	v_exp_f32_e32 v33, v29
	v_add_f32_e32 v28, 1.0, v30
	v_add_f32_e32 v29, 1.0, v31
	v_add_f32_e32 v30, 1.0, v32
	v_add_f32_e32 v31, 1.0, v33
	v_rcp_f32_e32 v28, v28
	v_rcp_f32_e32 v29, v29
	v_rcp_f32_e32 v30, v30
	v_rcp_f32_e32 v31, v31
	v_mul_f32_e32 v34, v243, v243
	v_pk_mul_f32 v[16:17], v[16:17], v[34:35] op_sel_hi:[1,0]
	v_pk_mul_f32 v[18:19], v[18:19], v[34:35] op_sel_hi:[1,0]
	v_pk_mul_f32 v[24:25], v[24:25], v[34:35] op_sel_hi:[1,0]
	v_pk_mul_f32 v[26:27], v[26:27], v[34:35] op_sel_hi:[1,0]
	v_pk_mul_f32 v[20:21], v[18:19], v[30:31]
	v_pk_mul_f32 v[18:19], v[16:17], v[28:29]
	v_add_u32_e32 v22, 0xa0, v181
	v_pk_mul_f32 v[26:27], v[26:27], v[38:39]
	v_pk_mul_f32 v[24:25], v[24:25], v[36:37]
	s_nop 0
	v_cvt_pk_bf16_f32 v16, v24, v25
	v_cvt_pk_bf16_f32 v17, v26, v27
	v_cvt_pk_bf16_f32 v18, v18, v19
	v_cvt_pk_bf16_f32 v19, v20, v21
	v_mad_i64_i32 v[20:21], s[0:1], v22, s45, v[112:113]
	v_lshl_add_u64 v[20:21], v[20:21], 0, v[114:115]
	global_store_dwordx4 v[20:21], v[16:19], off
	s_nop 1
	v_mul_f32_e32 v16, 0xbfb8aa3b, v248
	v_pk_mul_f32 v[22:23], v[12:13], v[16:17] op_sel_hi:[1,0]
	v_pk_mul_f32 v[20:21], v[14:15], v[16:17] op_sel_hi:[1,0]
	v_exp_f32_e32 v17, v22
	v_exp_f32_e32 v19, v23
	v_exp_f32_e32 v22, v20
	v_exp_f32_e32 v23, v21
	v_add_f32_e32 v17, 1.0, v17
	v_rcp_f32_e32 v20, v17
	v_add_f32_e32 v17, 1.0, v19
	v_rcp_f32_e32 v21, v17
	v_add_f32_e32 v17, 1.0, v22
	v_rcp_f32_e32 v22, v17
	v_add_f32_e32 v17, 1.0, v23
	v_pk_mul_f32 v[12:13], v[6:7], v[16:17] op_sel_hi:[1,0]
	v_pk_mul_f32 v[14:15], v[4:5], v[16:17] op_sel_hi:[1,0]
	v_rcp_f32_e32 v23, v17
	v_exp_f32_e32 v14, v14
	v_exp_f32_e32 v15, v15
	v_exp_f32_e32 v16, v12
	v_exp_f32_e32 v17, v13
	v_add_f32_e32 v12, 1.0, v14
	v_add_f32_e32 v13, 1.0, v15
	v_add_f32_e32 v14, 1.0, v16
	v_add_f32_e32 v15, 1.0, v17
	v_rcp_f32_e32 v12, v12
	v_rcp_f32_e32 v13, v13
	v_rcp_f32_e32 v14, v14
	v_rcp_f32_e32 v15, v15
	v_mul_f32_e32 v18, v248, v248
	v_pk_mul_f32 v[0:1], v[0:1], v[18:19] op_sel_hi:[1,0]
	v_pk_mul_f32 v[2:3], v[2:3], v[18:19] op_sel_hi:[1,0]
	v_pk_mul_f32 v[8:9], v[8:9], v[18:19] op_sel_hi:[1,0]
	v_pk_mul_f32 v[10:11], v[10:11], v[18:19] op_sel_hi:[1,0]
	v_pk_mul_f32 v[4:5], v[2:3], v[14:15]
	v_pk_mul_f32 v[2:3], v[0:1], v[12:13]
	v_add_u32_e32 v6, 0xb0, v181
	v_pk_mul_f32 v[10:11], v[10:11], v[22:23]
	v_pk_mul_f32 v[8:9], v[8:9], v[20:21]
	s_nop 0
	v_cvt_pk_bf16_f32 v0, v8, v9
	v_cvt_pk_bf16_f32 v1, v10, v11
	v_cvt_pk_bf16_f32 v2, v2, v3
	v_cvt_pk_bf16_f32 v3, v4, v5
	v_mad_i64_i32 v[4:5], s[0:1], v6, s45, v[112:113]
	v_lshl_add_u64 v[4:5], v[4:5], 0, v[114:115]
	s_mov_b64 s[0:1], -1
	global_store_dwordx4 v[4:5], v[0:3], off
	s_cbranch_vccnz .LBB0_628
	s_andn2_b64 vcc, exec, s[8:9]
	s_cbranch_vccnz .LBB0_627
	s_barrier
	s_branch .LBB0_627

.LBB0_805:
	s_or_b64 exec, exec, s[0:1]
	s_waitcnt lgkmcnt(7)
	v_add_f32_e32 v112, v173, v174
	v_fmamk_f32 v112, v112, 0x3a000000, v156
	v_rsq_f32_e32 v232, v112
	s_waitcnt lgkmcnt(0)
	v_mov_b32_e32 v114, v232
	v_pk_mul_f32 v[110:111], v[110:111], v[114:115] op_sel_hi:[1,0]
	v_pk_mul_f32 v[108:109], v[108:109], v[114:115] op_sel_hi:[1,0]
	v_pk_mul_f32 v[116:117], v[106:107], v[114:115] op_sel_hi:[1,0]
	v_pk_mul_f32 v[106:107], v[104:105], v[114:115] op_sel_hi:[1,0]
	v_mul_f32_e32 v104, v109, v109
	v_mul_f32_e32 v105, v111, v111
	v_fmac_f32_e32 v104, v108, v108
	v_fmac_f32_e32 v105, v110, v110
	v_add_f32_e32 v104, v104, v105
	v_mul_f32_e32 v105, v107, v107
	v_mul_f32_e32 v113, v117, v117
	v_fmac_f32_e32 v105, v106, v106
	v_fmac_f32_e32 v113, v116, v116
	v_add_f32_e32 v105, v105, v113
	v_pk_mul_f32 v[102:103], v[102:103], v[114:115] op_sel_hi:[1,0]
	v_pk_mul_f32 v[100:101], v[100:101], v[114:115] op_sel_hi:[1,0]
	v_add_f32_e32 v113, v104, v105
	v_cvt_pk_bf16_f32 v104, v108, v109
	v_cvt_pk_bf16_f32 v105, v110, v111
	v_pk_mul_f32 v[110:111], v[98:99], v[114:115] op_sel_hi:[1,0]
	v_pk_mul_f32 v[114:115], v[96:97], v[114:115] op_sel_hi:[1,0]
	v_mul_f32_e32 v96, v101, v101
	v_mul_f32_e32 v97, v103, v103
	v_fmac_f32_e32 v96, v100, v100
	v_fmac_f32_e32 v97, v102, v102
	v_add_f32_e32 v96, v96, v97
	v_mul_f32_e32 v97, v115, v115
	v_mul_f32_e32 v98, v111, v111
	v_fmac_f32_e32 v97, v114, v114
	v_fmac_f32_e32 v98, v110, v110
	v_add_f32_e32 v97, v97, v98
	v_add_f32_e32 v96, v96, v97
	v_add_f32_e32 v99, v113, v96
	ds_bpermute_b32 v113, v159, v99
	v_add_u32_e32 v112, 16, v160
	v_mov_b64_e32 v[108:109], s[68:69]
	v_mad_i64_i32 v[96:97], s[0:1], v112, s49, v[108:109]
	v_lshl_add_u64 v[108:109], v[146:147], 1, v[96:97]
	s_waitcnt lgkmcnt(0)
	v_add_f32_e32 v96, v99, v113
	ds_bpermute_b32 v97, v158, v96
	v_cvt_pk_bf16_f32 v106, v106, v107
	v_cvt_pk_bf16_f32 v107, v116, v117
	global_store_dwordx4 v[108:109], v[104:107], off
	v_cvt_pk_bf16_f32 v98, v100, v101
	v_cvt_pk_bf16_f32 v99, v102, v103
	v_cvt_pk_bf16_f32 v100, v114, v115
	v_cvt_pk_bf16_f32 v101, v110, v111
	global_store_dwordx4 v[108:109], v[98:101], off offset:256
	s_and_saveexec_b64 s[0:1], s[26:27]
	s_cbranch_execz .LBB0_807
	v_lshl_add_u32 v136, v112, 4, s15
	s_waitcnt lgkmcnt(0)
	v_add_f32_e32 v98, v96, v97
	v_lshl_add_u64 v[96:97], v[136:137], 2, s[8:9]
	global_store_dword v[96:97], v98, off
.LBB0_807:
	s_or_b64 exec, exec, s[0:1]
	v_add_f32_e32 v96, v171, v172
	v_fmamk_f32 v96, v96, 0x3a000000, v156
	v_rsq_f32_e32 v232, v96
	s_waitcnt lgkmcnt(0)
	v_mov_b32_e32 v98, v232
	v_pk_mul_f32 v[94:95], v[94:95], v[98:99] op_sel_hi:[1,0]
	v_pk_mul_f32 v[92:93], v[92:93], v[98:99] op_sel_hi:[1,0]
	v_pk_mul_f32 v[100:101], v[90:91], v[98:99] op_sel_hi:[1,0]
	v_pk_mul_f32 v[90:91], v[88:89], v[98:99] op_sel_hi:[1,0]
	v_mul_f32_e32 v88, v93, v93
	v_mul_f32_e32 v89, v95, v95
	v_fmac_f32_e32 v88, v92, v92
	v_fmac_f32_e32 v89, v94, v94
	v_add_f32_e32 v88, v88, v89
	v_mul_f32_e32 v89, v91, v91
	v_mul_f32_e32 v97, v101, v101
	v_fmac_f32_e32 v89, v90, v90
	v_fmac_f32_e32 v97, v100, v100
	v_add_f32_e32 v89, v89, v97
	v_pk_mul_f32 v[86:87], v[86:87], v[98:99] op_sel_hi:[1,0]
	v_pk_mul_f32 v[84:85], v[84:85], v[98:99] op_sel_hi:[1,0]
	v_add_f32_e32 v97, v88, v89
	v_cvt_pk_bf16_f32 v88, v92, v93
	v_cvt_pk_bf16_f32 v89, v94, v95
	v_pk_mul_f32 v[94:95], v[82:83], v[98:99] op_sel_hi:[1,0]
	v_pk_mul_f32 v[98:99], v[80:81], v[98:99] op_sel_hi:[1,0]
	v_mul_f32_e32 v80, v85, v85
	v_mul_f32_e32 v81, v87, v87
	v_fmac_f32_e32 v80, v84, v84
	v_fmac_f32_e32 v81, v86, v86
	v_add_f32_e32 v80, v80, v81
	v_mul_f32_e32 v81, v99, v99
	v_mul_f32_e32 v82, v95, v95
	v_fmac_f32_e32 v81, v98, v98
	v_fmac_f32_e32 v82, v94, v94
	v_add_f32_e32 v81, v81, v82
	v_add_f32_e32 v80, v80, v81
	v_add_f32_e32 v83, v97, v80
	ds_bpermute_b32 v97, v159, v83
	v_add_u32_e32 v96, 32, v160
	v_mov_b64_e32 v[92:93], s[68:69]
	v_mad_i64_i32 v[80:81], s[0:1], v96, s49, v[92:93]
	v_lshl_add_u64 v[92:93], v[146:147], 1, v[80:81]
	s_waitcnt lgkmcnt(0)
	v_add_f32_e32 v80, v83, v97
	ds_bpermute_b32 v81, v158, v80
	v_cvt_pk_bf16_f32 v90, v90, v91
	v_cvt_pk_bf16_f32 v91, v100, v101
	global_store_dwordx4 v[92:93], v[88:91], off
	v_cvt_pk_bf16_f32 v82, v84, v85
	v_cvt_pk_bf16_f32 v83, v86, v87
	v_cvt_pk_bf16_f32 v84, v98, v99
	v_cvt_pk_bf16_f32 v85, v94, v95
	global_store_dwordx4 v[92:93], v[82:85], off offset:256
	s_and_saveexec_b64 s[0:1], s[26:27]
	s_cbranch_execz .LBB0_809
	v_lshl_add_u32 v136, v96, 4, s15
	s_waitcnt lgkmcnt(0)
	v_add_f32_e32 v82, v80, v81
	v_lshl_add_u64 v[80:81], v[136:137], 2, s[8:9]
	global_store_dword v[80:81], v82, off
.LBB0_809:
	s_or_b64 exec, exec, s[0:1]
	v_add_f32_e32 v80, v169, v170
	v_fmamk_f32 v80, v80, 0x3a000000, v156
	v_rsq_f32_e32 v232, v80
	s_waitcnt lgkmcnt(0)
	v_mov_b32_e32 v82, v232
	v_pk_mul_f32 v[78:79], v[78:79], v[82:83] op_sel_hi:[1,0]
	v_pk_mul_f32 v[76:77], v[76:77], v[82:83] op_sel_hi:[1,0]
	v_pk_mul_f32 v[84:85], v[74:75], v[82:83] op_sel_hi:[1,0]
	v_pk_mul_f32 v[74:75], v[72:73], v[82:83] op_sel_hi:[1,0]
	v_mul_f32_e32 v72, v77, v77
	v_mul_f32_e32 v73, v79, v79
	v_fmac_f32_e32 v72, v76, v76
	v_fmac_f32_e32 v73, v78, v78
	v_add_f32_e32 v72, v72, v73
	v_mul_f32_e32 v73, v75, v75
	v_mul_f32_e32 v81, v85, v85
	v_fmac_f32_e32 v73, v74, v74
	v_fmac_f32_e32 v81, v84, v84
	v_add_f32_e32 v73, v73, v81
	v_pk_mul_f32 v[70:71], v[70:71], v[82:83] op_sel_hi:[1,0]
	v_pk_mul_f32 v[68:69], v[68:69], v[82:83] op_sel_hi:[1,0]
	v_add_f32_e32 v81, v72, v73
	v_cvt_pk_bf16_f32 v72, v76, v77
	v_cvt_pk_bf16_f32 v73, v78, v79
	v_pk_mul_f32 v[78:79], v[66:67], v[82:83] op_sel_hi:[1,0]
	v_pk_mul_f32 v[82:83], v[64:65], v[82:83] op_sel_hi:[1,0]
	v_mul_f32_e32 v64, v69, v69
	v_mul_f32_e32 v65, v71, v71
	v_fmac_f32_e32 v64, v68, v68
	v_fmac_f32_e32 v65, v70, v70
	v_add_f32_e32 v64, v64, v65
	v_mul_f32_e32 v65, v83, v83
	v_mul_f32_e32 v66, v79, v79
	v_fmac_f32_e32 v65, v82, v82
	v_fmac_f32_e32 v66, v78, v78
	v_add_f32_e32 v65, v65, v66
	v_add_f32_e32 v64, v64, v65
	v_add_f32_e32 v67, v81, v64
	ds_bpermute_b32 v81, v159, v67
	v_add_u32_e32 v80, 48, v160
	v_mov_b64_e32 v[76:77], s[68:69]
	v_mad_i64_i32 v[64:65], s[0:1], v80, s49, v[76:77]
	v_lshl_add_u64 v[76:77], v[146:147], 1, v[64:65]
	s_waitcnt lgkmcnt(0)
	v_add_f32_e32 v64, v67, v81
	ds_bpermute_b32 v65, v158, v64
	v_cvt_pk_bf16_f32 v74, v74, v75
	v_cvt_pk_bf16_f32 v75, v84, v85
	global_store_dwordx4 v[76:77], v[72:75], off
	v_cvt_pk_bf16_f32 v66, v68, v69
	v_cvt_pk_bf16_f32 v67, v70, v71
	v_cvt_pk_bf16_f32 v68, v82, v83
	v_cvt_pk_bf16_f32 v69, v78, v79
	global_store_dwordx4 v[76:77], v[66:69], off offset:256
	s_and_saveexec_b64 s[0:1], s[26:27]
	s_cbranch_execz .LBB0_811
	v_lshl_add_u32 v136, v80, 4, s15
	s_waitcnt lgkmcnt(0)
	v_add_f32_e32 v66, v64, v65
	v_lshl_add_u64 v[64:65], v[136:137], 2, s[8:9]
	global_store_dword v[64:65], v66, off
.LBB0_811:
	s_or_b64 exec, exec, s[0:1]
	v_add_f32_e32 v64, v167, v168
	v_fmamk_f32 v64, v64, 0x3a000000, v156
	v_rsq_f32_e32 v232, v64
	s_waitcnt lgkmcnt(0)
	v_mov_b32_e32 v66, v232
	v_pk_mul_f32 v[62:63], v[62:63], v[66:67] op_sel_hi:[1,0]
	v_pk_mul_f32 v[60:61], v[60:61], v[66:67] op_sel_hi:[1,0]
	v_pk_mul_f32 v[68:69], v[58:59], v[66:67] op_sel_hi:[1,0]
	v_pk_mul_f32 v[58:59], v[56:57], v[66:67] op_sel_hi:[1,0]
	v_mul_f32_e32 v56, v61, v61
	v_mul_f32_e32 v57, v63, v63
	v_fmac_f32_e32 v56, v60, v60
	v_fmac_f32_e32 v57, v62, v62
	v_add_f32_e32 v56, v56, v57
	v_mul_f32_e32 v57, v59, v59
	v_mul_f32_e32 v65, v69, v69
	v_fmac_f32_e32 v57, v58, v58
	v_fmac_f32_e32 v65, v68, v68
	v_add_f32_e32 v57, v57, v65
	v_pk_mul_f32 v[54:55], v[54:55], v[66:67] op_sel_hi:[1,0]
	v_pk_mul_f32 v[52:53], v[52:53], v[66:67] op_sel_hi:[1,0]
	v_add_f32_e32 v65, v56, v57
	v_cvt_pk_bf16_f32 v56, v60, v61
	v_cvt_pk_bf16_f32 v57, v62, v63
	v_pk_mul_f32 v[62:63], v[50:51], v[66:67] op_sel_hi:[1,0]
	v_pk_mul_f32 v[66:67], v[48:49], v[66:67] op_sel_hi:[1,0]
	v_mul_f32_e32 v48, v53, v53
	v_mul_f32_e32 v49, v55, v55
	v_fmac_f32_e32 v48, v52, v52
	v_fmac_f32_e32 v49, v54, v54
	v_add_f32_e32 v48, v48, v49
	v_mul_f32_e32 v49, v67, v67
	v_mul_f32_e32 v50, v63, v63
	v_fmac_f32_e32 v49, v66, v66
	v_fmac_f32_e32 v50, v62, v62
	v_add_f32_e32 v49, v49, v50
	v_add_f32_e32 v48, v48, v49
	v_add_f32_e32 v51, v65, v48
	ds_bpermute_b32 v65, v159, v51
	v_add_u32_e32 v64, 0x80, v160
	v_mov_b64_e32 v[60:61], s[68:69]
	v_mad_i64_i32 v[48:49], s[0:1], v64, s49, v[60:61]
	v_lshl_add_u64 v[60:61], v[146:147], 1, v[48:49]
	s_waitcnt lgkmcnt(0)
	v_add_f32_e32 v48, v51, v65
	ds_bpermute_b32 v49, v158, v48
	v_cvt_pk_bf16_f32 v58, v58, v59
	v_cvt_pk_bf16_f32 v59, v68, v69
	global_store_dwordx4 v[60:61], v[56:59], off
	v_cvt_pk_bf16_f32 v50, v52, v53
	v_cvt_pk_bf16_f32 v51, v54, v55
	v_cvt_pk_bf16_f32 v52, v66, v67
	v_cvt_pk_bf16_f32 v53, v62, v63
	global_store_dwordx4 v[60:61], v[50:53], off offset:256
	s_and_saveexec_b64 s[0:1], s[26:27]
	s_cbranch_execz .LBB0_813
	v_lshl_add_u32 v136, v64, 4, s15
	s_waitcnt lgkmcnt(0)
	v_add_f32_e32 v50, v48, v49
	v_lshl_add_u64 v[48:49], v[136:137], 2, s[8:9]
	global_store_dword v[48:49], v50, off
.LBB0_813:
	s_or_b64 exec, exec, s[0:1]
	v_add_f32_e32 v48, v165, v166
	v_fmamk_f32 v48, v48, 0x3a000000, v156
	v_rsq_f32_e32 v232, v48
	s_waitcnt lgkmcnt(0)
	v_mov_b32_e32 v50, v232
	v_pk_mul_f32 v[46:47], v[46:47], v[50:51] op_sel_hi:[1,0]
	v_pk_mul_f32 v[44:45], v[44:45], v[50:51] op_sel_hi:[1,0]
	v_pk_mul_f32 v[52:53], v[42:43], v[50:51] op_sel_hi:[1,0]
	v_pk_mul_f32 v[42:43], v[40:41], v[50:51] op_sel_hi:[1,0]
	v_mul_f32_e32 v40, v45, v45
	v_mul_f32_e32 v41, v47, v47
	v_fmac_f32_e32 v40, v44, v44
	v_fmac_f32_e32 v41, v46, v46
	v_add_f32_e32 v40, v40, v41
	v_mul_f32_e32 v41, v43, v43
	v_mul_f32_e32 v49, v53, v53
	v_fmac_f32_e32 v41, v42, v42
	v_fmac_f32_e32 v49, v52, v52
	v_add_f32_e32 v41, v41, v49
	v_pk_mul_f32 v[38:39], v[38:39], v[50:51] op_sel_hi:[1,0]
	v_pk_mul_f32 v[36:37], v[36:37], v[50:51] op_sel_hi:[1,0]
	v_add_f32_e32 v49, v40, v41
	v_cvt_pk_bf16_f32 v40, v44, v45
	v_cvt_pk_bf16_f32 v41, v46, v47
	v_pk_mul_f32 v[46:47], v[34:35], v[50:51] op_sel_hi:[1,0]
	v_pk_mul_f32 v[50:51], v[32:33], v[50:51] op_sel_hi:[1,0]
	v_mul_f32_e32 v32, v37, v37
	v_mul_f32_e32 v33, v39, v39
	v_fmac_f32_e32 v32, v36, v36
	v_fmac_f32_e32 v33, v38, v38
	v_add_f32_e32 v32, v32, v33
	v_mul_f32_e32 v33, v51, v51
	v_mul_f32_e32 v34, v47, v47
	v_fmac_f32_e32 v33, v50, v50
	v_fmac_f32_e32 v34, v46, v46
	v_add_f32_e32 v33, v33, v34
	v_add_f32_e32 v32, v32, v33
	v_add_f32_e32 v35, v49, v32
	ds_bpermute_b32 v49, v159, v35
	v_add_u32_e32 v48, 0x90, v160
	v_mov_b64_e32 v[44:45], s[68:69]
	v_mad_i64_i32 v[32:33], s[0:1], v48, s49, v[44:45]
	v_lshl_add_u64 v[44:45], v[146:147], 1, v[32:33]
	s_waitcnt lgkmcnt(0)
	v_add_f32_e32 v32, v35, v49
	ds_bpermute_b32 v33, v158, v32
	v_cvt_pk_bf16_f32 v42, v42, v43
	v_cvt_pk_bf16_f32 v43, v52, v53
	global_store_dwordx4 v[44:45], v[40:43], off
	v_cvt_pk_bf16_f32 v34, v36, v37
	v_cvt_pk_bf16_f32 v35, v38, v39
	v_cvt_pk_bf16_f32 v36, v50, v51
	v_cvt_pk_bf16_f32 v37, v46, v47
	global_store_dwordx4 v[44:45], v[34:37], off offset:256
	s_and_saveexec_b64 s[0:1], s[26:27]
	s_cbranch_execz .LBB0_815
	v_lshl_add_u32 v136, v48, 4, s15
	s_waitcnt lgkmcnt(0)
	v_add_f32_e32 v34, v32, v33
	v_lshl_add_u64 v[32:33], v[136:137], 2, s[8:9]
	global_store_dword v[32:33], v34, off
.LBB0_815:
	s_or_b64 exec, exec, s[0:1]
	v_add_f32_e32 v32, v163, v164
	v_fmamk_f32 v32, v32, 0x3a000000, v156
	v_rsq_f32_e32 v232, v32
	s_waitcnt lgkmcnt(0)
	v_mov_b32_e32 v34, v232
	v_pk_mul_f32 v[30:31], v[30:31], v[34:35] op_sel_hi:[1,0]
	v_pk_mul_f32 v[28:29], v[28:29], v[34:35] op_sel_hi:[1,0]
	v_pk_mul_f32 v[36:37], v[26:27], v[34:35] op_sel_hi:[1,0]
	v_pk_mul_f32 v[26:27], v[24:25], v[34:35] op_sel_hi:[1,0]
	v_mul_f32_e32 v24, v29, v29
	v_mul_f32_e32 v25, v31, v31
	v_fmac_f32_e32 v24, v28, v28
	v_fmac_f32_e32 v25, v30, v30
	v_add_f32_e32 v24, v24, v25
	v_mul_f32_e32 v25, v27, v27
	v_mul_f32_e32 v33, v37, v37
	v_fmac_f32_e32 v25, v26, v26
	v_fmac_f32_e32 v33, v36, v36
	v_add_f32_e32 v25, v25, v33
	v_pk_mul_f32 v[22:23], v[22:23], v[34:35] op_sel_hi:[1,0]
	v_pk_mul_f32 v[20:21], v[20:21], v[34:35] op_sel_hi:[1,0]
	v_add_f32_e32 v33, v24, v25
	v_cvt_pk_bf16_f32 v24, v28, v29
	v_cvt_pk_bf16_f32 v25, v30, v31
	v_pk_mul_f32 v[30:31], v[18:19], v[34:35] op_sel_hi:[1,0]
	v_pk_mul_f32 v[34:35], v[16:17], v[34:35] op_sel_hi:[1,0]
	v_mul_f32_e32 v16, v21, v21
	v_mul_f32_e32 v17, v23, v23
	v_fmac_f32_e32 v16, v20, v20
	v_fmac_f32_e32 v17, v22, v22
	v_add_f32_e32 v16, v16, v17
	v_mul_f32_e32 v17, v35, v35
	v_mul_f32_e32 v18, v31, v31
	v_fmac_f32_e32 v17, v34, v34
	v_fmac_f32_e32 v18, v30, v30
	v_add_f32_e32 v17, v17, v18
	v_add_f32_e32 v16, v16, v17
	v_add_f32_e32 v19, v33, v16
	ds_bpermute_b32 v33, v159, v19
	v_add_u32_e32 v32, 0xa0, v160
	v_mov_b64_e32 v[28:29], s[68:69]
	v_mad_i64_i32 v[16:17], s[0:1], v32, s49, v[28:29]
	v_lshl_add_u64 v[28:29], v[146:147], 1, v[16:17]
	s_waitcnt lgkmcnt(0)
	v_add_f32_e32 v16, v19, v33
	ds_bpermute_b32 v17, v158, v16
	v_cvt_pk_bf16_f32 v26, v26, v27
	v_cvt_pk_bf16_f32 v27, v36, v37
	global_store_dwordx4 v[28:29], v[24:27], off
	v_cvt_pk_bf16_f32 v18, v20, v21
	v_cvt_pk_bf16_f32 v19, v22, v23
	v_cvt_pk_bf16_f32 v20, v34, v35
	v_cvt_pk_bf16_f32 v21, v30, v31
	global_store_dwordx4 v[28:29], v[18:21], off offset:256
	s_and_saveexec_b64 s[0:1], s[26:27]
	s_cbranch_execz .LBB0_817
	v_lshl_add_u32 v136, v32, 4, s15
	s_waitcnt lgkmcnt(0)
	v_add_f32_e32 v18, v16, v17
	v_lshl_add_u64 v[16:17], v[136:137], 2, s[8:9]
	global_store_dword v[16:17], v18, off
.LBB0_817:
	s_or_b64 exec, exec, s[0:1]
	v_add_f32_e32 v16, v161, v162
	v_fmamk_f32 v16, v16, 0x3a000000, v156
	v_rsq_f32_e32 v232, v16
	s_waitcnt lgkmcnt(0)
	v_mov_b32_e32 v18, v232
	v_pk_mul_f32 v[14:15], v[14:15], v[18:19] op_sel_hi:[1,0]
	v_pk_mul_f32 v[12:13], v[12:13], v[18:19] op_sel_hi:[1,0]
	v_pk_mul_f32 v[20:21], v[10:11], v[18:19] op_sel_hi:[1,0]
	v_pk_mul_f32 v[10:11], v[8:9], v[18:19] op_sel_hi:[1,0]
	v_mul_f32_e32 v8, v13, v13
	v_mul_f32_e32 v9, v15, v15
	v_fmac_f32_e32 v8, v12, v12
	v_fmac_f32_e32 v9, v14, v14
	v_add_f32_e32 v8, v8, v9
	v_mul_f32_e32 v9, v11, v11
	v_mul_f32_e32 v17, v21, v21
	v_fmac_f32_e32 v9, v10, v10
	v_fmac_f32_e32 v17, v20, v20
	v_add_f32_e32 v9, v9, v17
	v_pk_mul_f32 v[6:7], v[6:7], v[18:19] op_sel_hi:[1,0]
	v_pk_mul_f32 v[4:5], v[4:5], v[18:19] op_sel_hi:[1,0]
	v_add_f32_e32 v17, v8, v9
	v_cvt_pk_bf16_f32 v8, v12, v13
	v_cvt_pk_bf16_f32 v9, v14, v15
	v_pk_mul_f32 v[14:15], v[2:3], v[18:19] op_sel_hi:[1,0]
	v_pk_mul_f32 v[18:19], v[0:1], v[18:19] op_sel_hi:[1,0]
	v_mul_f32_e32 v0, v5, v5
	v_mul_f32_e32 v1, v7, v7
	v_fmac_f32_e32 v0, v4, v4
	v_fmac_f32_e32 v1, v6, v6
	v_add_f32_e32 v0, v0, v1
	v_mul_f32_e32 v1, v19, v19
	v_mul_f32_e32 v2, v15, v15
	v_fmac_f32_e32 v1, v18, v18
	v_fmac_f32_e32 v2, v14, v14
	v_add_f32_e32 v1, v1, v2
	v_add_f32_e32 v0, v0, v1
	v_add_f32_e32 v3, v17, v0
	ds_bpermute_b32 v17, v159, v3
	v_add_u32_e32 v16, 0xb0, v160
	v_mov_b64_e32 v[12:13], s[68:69]
	v_mad_i64_i32 v[0:1], s[0:1], v16, s49, v[12:13]
	v_lshl_add_u64 v[12:13], v[146:147], 1, v[0:1]
	s_waitcnt lgkmcnt(0)
	v_add_f32_e32 v0, v3, v17
	ds_bpermute_b32 v1, v158, v0
	v_cvt_pk_bf16_f32 v10, v10, v11
	v_cvt_pk_bf16_f32 v11, v20, v21
	global_store_dwordx4 v[12:13], v[8:11], off
	v_cvt_pk_bf16_f32 v2, v4, v5
	v_cvt_pk_bf16_f32 v3, v6, v7
	v_cvt_pk_bf16_f32 v4, v18, v19
	v_cvt_pk_bf16_f32 v5, v14, v15
	global_store_dwordx4 v[12:13], v[2:5], off offset:256
	s_and_saveexec_b64 s[0:1], s[26:27]
	s_cbranch_execz .LBB0_819
	v_lshl_add_u32 v136, v16, 4, s15
	s_waitcnt lgkmcnt(0)
	v_add_f32_e32 v2, v0, v1
	v_lshl_add_u64 v[0:1], v[136:137], 2, s[8:9]
	global_store_dword v[0:1], v2, off

.LBB0_899:
	s_lshl_b32 s0, s34, 8
	s_add_i32 s0, s0, s44
	v_mov_b32_e32 v104, v212
	v_mov_b32_e32 v205, v213
	s_cmp_gt_i32 s26, 15
	s_cselect_b64 s[36:37], -1, 0
	v_add_u32_e32 v204, s0, v104
	s_lshl_b32 s0, s26, 8
	s_add_i32 s28, s0, 0xfffff000
	s_mul_i32 s34, s26, 0xc0
	s_ashr_i32 s29, s28, 31
	s_ashr_i32 s35, s34, 31
	s_cmp_lt_i32 s26, 16
	s_cselect_b64 s[0:1], -1, 0
	s_and_b64 s[6:7], s[0:1], exec
	v_readlane_b32 s0, v254, 25
	s_cselect_b32 s19, 0, 32
	v_readlane_b32 s1, v254, 26
	s_cselect_b32 s30, s57, s0
	s_cselect_b32 s31, s62, s1
	s_cselect_b32 s0, s34, s28
	s_cselect_b32 s1, s35, s29
	s_add_u32 s38, s8, s19
	s_addc_u32 s39, s9, 0
	v_lshlrev_b32_e32 v194, 4, v204
	v_lshl_add_u64 v[104:105], v[194:195], 2, s[38:39]
	global_load_dwordx4 v[220:223], v[104:105], off
	global_load_dwordx4 v[224:227], v[104:105], off offset:16
	v_mov_b32_e32 v105, v195
	v_mov_b32_e32 v125, v195
	v_mov_b32_e32 v127, v195
	v_add_u32_e32 v104, 0x100, v194
	v_add_u32_e32 v124, 0x900, v194
	v_add_u32_e32 v126, 0xa00, v194
	v_mov_b32_e32 v107, v195
	v_mov_b32_e32 v109, v195
	v_mov_b32_e32 v111, v195
	v_add_u32_e32 v106, 0x200, v194
	v_add_u32_e32 v108, 0x300, v194
	v_add_u32_e32 v110, 0x800, v194
	v_lshl_add_u64 v[104:105], v[104:105], 2, s[38:39]
	v_lshl_add_u64 v[124:125], v[124:125], 2, s[38:39]
	v_lshl_add_u64 v[132:133], v[126:127], 2, s[38:39]
	v_lshl_add_u64 v[106:107], v[106:107], 2, s[38:39]
	v_lshl_add_u64 v[108:109], v[108:109], 2, s[38:39]
	v_lshl_add_u64 v[110:111], v[110:111], 2, s[38:39]
	global_load_dwordx4 v[176:179], v[104:105], off offset:16
	global_load_dwordx4 v[180:183], v[104:105], off
	global_load_dwordx4 v[168:171], v[106:107], off offset:16
	global_load_dwordx4 v[172:175], v[106:107], off
	global_load_dwordx4 v[160:163], v[108:109], off offset:16
	global_load_dwordx4 v[164:167], v[108:109], off
	global_load_dwordx4 v[152:155], v[110:111], off offset:16
	global_load_dwordx4 v[156:159], v[110:111], off
	global_load_dwordx4 v[144:147], v[124:125], off offset:16
	global_load_dwordx4 v[148:151], v[124:125], off
	s_nop 0
	global_load_dwordx4 v[124:127], v[132:133], off offset:16
	s_nop 0
	global_load_dwordx4 v[132:135], v[132:133], off
	v_add_u32_e32 v194, 0xb00, v194
	v_lshl_add_u64 v[108:109], v[194:195], 2, s[38:39]
	global_load_dwordx4 v[104:107], v[108:109], off offset:16
	s_nop 0
	global_load_dwordx4 v[108:111], v[108:109], off
	v_lshl_add_u32 v206, v205, 3, s45
	v_mov_b64_e32 v[210:211], s[30:31]
	v_mad_i64_i32 v[210:211], s[60:61], v204, s55, v[210:211]
	v_lshl_add_u64 v[210:211], s[0:1], 1, v[210:211]
	v_ashrrev_i32_e32 v207, 31, v206
	s_mov_b64 s[38:39], -1
	s_waitcnt vmcnt(0)
	v_mov_b32_e32 v228, v220
	v_mov_b32_e32 v229, v224
	v_mov_b32_e32 v224, v221
	v_mov_b32_e32 v220, v222
	v_mov_b32_e32 v221, v226
	v_mov_b32_e32 v226, v223
	v_pk_add_f32 v[222:223], v[228:229], v[224:225]
	v_pk_add_f32 v[220:221], v[220:221], v[226:227]
	s_nop 0
	v_pk_add_f32 v[220:221], v[222:223], v[220:221]
	s_nop 0
	v_add_f32_e32 v194, v220, v221
	v_fmamk_f32 v194, v194, 0x3b000000, v218
	v_rsq_f32_e32 v232, v194
	v_lshl_add_u64 v[220:221], v[206:207], 1, v[210:211]
	v_mov_b32_e32 v210, v232
	v_pk_mul_f32 v[222:223], v[138:139], v[210:211] op_sel_hi:[1,0]
	v_pk_mul_f32 v[138:139], v[136:137], v[210:211] op_sel_hi:[1,0]
	s_mov_b64 vcc, s[6:7]
	v_pk_mul_f32 v[142:143], v[142:143], v[210:211] op_sel_hi:[1,0]
	v_pk_mul_f32 v[140:141], v[140:141], v[210:211] op_sel_hi:[1,0]
	s_nop 0
	v_cvt_pk_bf16_f32 v136, v140, v141
	v_cvt_pk_bf16_f32 v137, v142, v143
	v_cvt_pk_bf16_f32 v138, v138, v139
	v_cvt_pk_bf16_f32 v139, v222, v223
	global_store_dwordx4 v[220:221], v[136:139], off
	s_cbranch_vccnz .LBB0_901
	s_nop 0
	v_mad_i64_i32 v[136:137], s[0:1], v204, s55, 0
	v_readlane_b32 s0, v254, 25
	v_readlane_b32 s1, v254, 26
	s_mov_b64 s[38:39], 0
	s_nop 0
	v_lshl_add_u64 v[136:137], s[0:1], 0, v[136:137]
	v_lshl_add_u64 v[136:137], s[28:29], 1, v[136:137]
	v_lshl_add_u64 v[208:209], v[136:137], 0, s[16:17]

.LBB0_903:
	v_mov_b32_e32 v211, v210
	v_mov_b32_e32 v140, v210
	v_mov_b32_e32 v141, v210
	v_pk_mul_f32 v[130:131], v[130:131], v[140:141]
	v_pk_mul_f32 v[140:141], v[122:123], v[140:141]
	v_pk_mul_f32 v[122:123], v[120:121], v[210:211]
	v_mov_b32_e32 v120, v180
	v_mov_b32_e32 v121, v176
	v_mov_b32_e32 v176, v181
	v_mov_b32_e32 v142, v182
	v_mov_b32_e32 v143, v178
	v_mov_b32_e32 v178, v183
	v_pk_add_f32 v[120:121], v[120:121], v[176:177]
	v_pk_add_f32 v[142:143], v[142:143], v[178:179]
	v_pk_mul_f32 v[128:129], v[128:129], v[210:211]
	v_pk_add_f32 v[120:121], v[120:121], v[142:143]
	v_lshlrev_b64 v[136:137], 1, v[206:207]
	v_add_f32_e32 v120, v120, v121
	v_fmamk_f32 v120, v120, 0x3b000000, v218
	v_rsq_f32_e32 v232, v120
	v_lshl_add_u64 v[138:139], v[208:209], 0, v[136:137]
	v_cvt_pk_bf16_f32 v120, v128, v129
	v_cvt_pk_bf16_f32 v121, v130, v131
	v_cvt_pk_bf16_f32 v122, v122, v123
	v_cvt_pk_bf16_f32 v123, v140, v141
	global_store_dwordx4 v[138:139], v[120:123], off
	s_nop 1
	v_add_u32_e32 v122, 16, v204
	v_mov_b32_e32 v120, v232
	v_mov_b64_e32 v[128:129], s[30:31]
	v_mad_i64_i32 v[128:129], s[0:1], v122, s55, v[128:129]
	v_lshl_add_u64 v[128:129], s[6:7], 1, v[128:129]
	v_lshl_add_u64 v[128:129], v[128:129], 0, v[136:137]
	v_pk_mul_f32 v[116:117], v[116:117], v[120:121] op_sel_hi:[1,0]
	v_pk_mul_f32 v[130:131], v[114:115], v[120:121] op_sel_hi:[1,0]
	v_pk_mul_f32 v[114:115], v[112:113], v[120:121] op_sel_hi:[1,0]
	v_cvt_pk_bf16_f32 v112, v116, v117
	v_pk_mul_f32 v[118:119], v[118:119], v[120:121] op_sel_hi:[1,0]
	s_andn2_b64 vcc, exec, s[36:37]
	v_cvt_pk_bf16_f32 v113, v118, v119
	v_cvt_pk_bf16_f32 v114, v114, v115
	v_cvt_pk_bf16_f32 v115, v130, v131
	global_store_dwordx4 v[128:129], v[112:115], off
	s_mov_b64 s[0:1], -1
	s_nop 0
	v_cndmask_b32_e64 v112, 0, 1, s[36:37]
	v_cmp_ne_u32_e64 s[6:7], 1, v112
	s_cbranch_vccnz .LBB0_905
	v_mad_i64_i32 v[112:113], s[0:1], v122, s55, 0
	v_readlane_b32 s0, v254, 25
	v_readlane_b32 s1, v254, 26
	s_nop 1
	v_lshl_add_u64 v[112:113], s[0:1], 0, v[112:113]
	v_lshl_add_u64 v[112:113], s[28:29], 1, v[112:113]
	v_lshl_add_u64 v[112:113], v[112:113], 0, s[16:17]
	s_mov_b64 s[0:1], 0

.LBB0_907:
	v_mov_b32_e32 v121, v120
	v_mov_b32_e32 v114, v120
	v_mov_b32_e32 v115, v120
	v_pk_mul_f32 v[102:103], v[102:103], v[114:115]
	v_pk_mul_f32 v[114:115], v[98:99], v[114:115]
	v_pk_mul_f32 v[98:99], v[96:97], v[120:121]
	v_mov_b32_e32 v96, v172
	v_mov_b32_e32 v97, v168
	v_mov_b32_e32 v168, v173
	v_mov_b32_e32 v116, v174
	v_mov_b32_e32 v117, v170
	v_mov_b32_e32 v170, v175
	v_pk_add_f32 v[96:97], v[96:97], v[168:169]
	v_pk_add_f32 v[116:117], v[116:117], v[170:171]
	v_pk_mul_f32 v[100:101], v[100:101], v[120:121]
	v_pk_add_f32 v[96:97], v[96:97], v[116:117]
	v_lshl_add_u64 v[112:113], v[112:113], 0, v[136:137]
	v_add_f32_e32 v96, v96, v97
	v_fmamk_f32 v96, v96, 0x3b000000, v218
	v_rsq_f32_e32 v232, v96
	v_cvt_pk_bf16_f32 v96, v100, v101
	v_cvt_pk_bf16_f32 v97, v102, v103
	v_cvt_pk_bf16_f32 v98, v98, v99
	v_cvt_pk_bf16_f32 v99, v114, v115
	global_store_dwordx4 v[112:113], v[96:99], off
	s_nop 1
	v_add_u32_e32 v98, 32, v204
	v_mov_b32_e32 v96, v232
	v_mov_b64_e32 v[100:101], s[30:31]
	v_mad_i64_i32 v[100:101], s[0:1], v98, s55, v[100:101]
	v_lshl_add_u64 v[100:101], s[36:37], 1, v[100:101]
	v_lshl_add_u64 v[100:101], v[100:101], 0, v[136:137]
	v_pk_mul_f32 v[94:95], v[94:95], v[96:97] op_sel_hi:[1,0]
	v_pk_mul_f32 v[92:93], v[92:93], v[96:97] op_sel_hi:[1,0]
	v_pk_mul_f32 v[102:103], v[90:91], v[96:97] op_sel_hi:[1,0]
	v_pk_mul_f32 v[90:91], v[88:89], v[96:97] op_sel_hi:[1,0]
	v_cvt_pk_bf16_f32 v88, v92, v93
	v_cvt_pk_bf16_f32 v89, v94, v95
	s_and_b64 vcc, exec, s[6:7]
	s_mov_b64 s[0:1], -1
	v_cvt_pk_bf16_f32 v90, v90, v91
	v_cvt_pk_bf16_f32 v91, v102, v103
	global_store_dwordx4 v[100:101], v[88:91], off
	s_cbranch_vccnz .LBB0_909
	s_nop 0
	v_mad_i64_i32 v[88:89], s[0:1], v98, s55, 0
	v_readlane_b32 s0, v254, 25
	v_readlane_b32 s1, v254, 26
	s_nop 1
	v_lshl_add_u64 v[88:89], s[0:1], 0, v[88:89]
	v_lshl_add_u64 v[88:89], s[28:29], 1, v[88:89]
	v_lshl_add_u64 v[88:89], v[88:89], 0, s[16:17]
	s_mov_b64 s[0:1], 0

.LBB0_911:
	v_mov_b32_e32 v97, v96
	v_mov_b32_e32 v90, v96
	v_mov_b32_e32 v91, v96
	v_pk_mul_f32 v[86:87], v[86:87], v[90:91]
	v_pk_mul_f32 v[90:91], v[82:83], v[90:91]
	v_pk_mul_f32 v[82:83], v[80:81], v[96:97]
	v_mov_b32_e32 v80, v164
	v_mov_b32_e32 v81, v160
	v_mov_b32_e32 v160, v165
	v_mov_b32_e32 v92, v166
	v_mov_b32_e32 v93, v162
	v_mov_b32_e32 v162, v167
	v_pk_add_f32 v[80:81], v[80:81], v[160:161]
	v_pk_add_f32 v[92:93], v[92:93], v[162:163]
	v_pk_mul_f32 v[84:85], v[84:85], v[96:97]
	v_pk_add_f32 v[80:81], v[80:81], v[92:93]
	v_lshl_add_u64 v[88:89], v[88:89], 0, v[136:137]
	v_add_f32_e32 v80, v80, v81
	v_fmamk_f32 v80, v80, 0x3b000000, v218
	v_rsq_f32_e32 v232, v80
	v_cvt_pk_bf16_f32 v80, v84, v85
	v_cvt_pk_bf16_f32 v81, v86, v87
	v_cvt_pk_bf16_f32 v82, v82, v83
	v_cvt_pk_bf16_f32 v83, v90, v91
	global_store_dwordx4 v[88:89], v[80:83], off
	s_nop 1
	v_add_u32_e32 v82, 48, v204
	v_mov_b32_e32 v80, v232
	v_mov_b64_e32 v[84:85], s[30:31]
	v_mad_i64_i32 v[84:85], s[0:1], v82, s55, v[84:85]
	v_lshl_add_u64 v[84:85], s[36:37], 1, v[84:85]
	v_lshl_add_u64 v[84:85], v[84:85], 0, v[136:137]
	v_pk_mul_f32 v[78:79], v[78:79], v[80:81] op_sel_hi:[1,0]
	v_pk_mul_f32 v[76:77], v[76:77], v[80:81] op_sel_hi:[1,0]
	v_pk_mul_f32 v[86:87], v[74:75], v[80:81] op_sel_hi:[1,0]
	v_pk_mul_f32 v[74:75], v[72:73], v[80:81] op_sel_hi:[1,0]
	v_cvt_pk_bf16_f32 v72, v76, v77
	v_cvt_pk_bf16_f32 v73, v78, v79
	s_and_b64 vcc, exec, s[6:7]
	s_mov_b64 s[0:1], -1
	v_cvt_pk_bf16_f32 v74, v74, v75
	v_cvt_pk_bf16_f32 v75, v86, v87
	global_store_dwordx4 v[84:85], v[72:75], off
	s_cbranch_vccnz .LBB0_913
	s_nop 0
	v_mad_i64_i32 v[72:73], s[0:1], v82, s55, 0
	v_readlane_b32 s0, v254, 25
	v_readlane_b32 s1, v254, 26
	s_nop 1
	v_lshl_add_u64 v[72:73], s[0:1], 0, v[72:73]
	v_lshl_add_u64 v[72:73], s[28:29], 1, v[72:73]
	v_lshl_add_u64 v[72:73], v[72:73], 0, s[16:17]
	s_mov_b64 s[0:1], 0

.LBB0_915:
	v_mov_b32_e32 v81, v80
	v_mov_b32_e32 v74, v80
	v_mov_b32_e32 v75, v80
	v_pk_mul_f32 v[70:71], v[70:71], v[74:75]
	v_pk_mul_f32 v[74:75], v[66:67], v[74:75]
	v_pk_mul_f32 v[66:67], v[64:65], v[80:81]
	v_mov_b32_e32 v64, v156
	v_mov_b32_e32 v65, v152
	v_mov_b32_e32 v152, v157
	v_mov_b32_e32 v76, v158
	v_mov_b32_e32 v77, v154
	v_mov_b32_e32 v154, v159
	v_pk_add_f32 v[64:65], v[64:65], v[152:153]
	v_pk_add_f32 v[76:77], v[76:77], v[154:155]
	v_pk_mul_f32 v[68:69], v[68:69], v[80:81]
	v_pk_add_f32 v[64:65], v[64:65], v[76:77]
	v_lshl_add_u64 v[72:73], v[72:73], 0, v[136:137]
	v_add_f32_e32 v64, v64, v65
	v_fmamk_f32 v64, v64, 0x3b000000, v218
	v_rsq_f32_e32 v232, v64
	v_cvt_pk_bf16_f32 v64, v68, v69
	v_cvt_pk_bf16_f32 v65, v70, v71
	v_cvt_pk_bf16_f32 v66, v66, v67
	v_cvt_pk_bf16_f32 v67, v74, v75
	global_store_dwordx4 v[72:73], v[64:67], off
	s_nop 1
	v_add_u32_e32 v66, 0x80, v204
	v_mov_b32_e32 v64, v232
	v_mov_b64_e32 v[68:69], s[30:31]
	v_mad_i64_i32 v[68:69], s[0:1], v66, s55, v[68:69]
	v_lshl_add_u64 v[68:69], s[36:37], 1, v[68:69]
	v_lshl_add_u64 v[68:69], v[68:69], 0, v[136:137]
	v_pk_mul_f32 v[62:63], v[62:63], v[64:65] op_sel_hi:[1,0]
	v_pk_mul_f32 v[60:61], v[60:61], v[64:65] op_sel_hi:[1,0]
	v_pk_mul_f32 v[70:71], v[58:59], v[64:65] op_sel_hi:[1,0]
	v_pk_mul_f32 v[58:59], v[56:57], v[64:65] op_sel_hi:[1,0]
	v_cvt_pk_bf16_f32 v56, v60, v61
	v_cvt_pk_bf16_f32 v57, v62, v63
	s_and_b64 vcc, exec, s[6:7]
	s_mov_b64 s[0:1], -1
	v_cvt_pk_bf16_f32 v58, v58, v59
	v_cvt_pk_bf16_f32 v59, v70, v71
	global_store_dwordx4 v[68:69], v[56:59], off
	s_cbranch_vccnz .LBB0_917
	s_nop 0
	v_mad_i64_i32 v[56:57], s[0:1], v66, s55, 0
	v_readlane_b32 s0, v254, 25
	v_readlane_b32 s1, v254, 26
	s_nop 1
	v_lshl_add_u64 v[56:57], s[0:1], 0, v[56:57]
	v_lshl_add_u64 v[56:57], s[28:29], 1, v[56:57]
	v_lshl_add_u64 v[56:57], v[56:57], 0, s[16:17]
	s_mov_b64 s[0:1], 0

.LBB0_919:
	v_mov_b32_e32 v65, v64
	v_mov_b32_e32 v58, v64
	v_mov_b32_e32 v59, v64
	v_pk_mul_f32 v[54:55], v[54:55], v[58:59]
	v_pk_mul_f32 v[58:59], v[50:51], v[58:59]
	v_pk_mul_f32 v[50:51], v[48:49], v[64:65]
	v_mov_b32_e32 v48, v148
	v_mov_b32_e32 v49, v144
	v_mov_b32_e32 v144, v149
	v_mov_b32_e32 v60, v150
	v_mov_b32_e32 v61, v146
	v_mov_b32_e32 v146, v151
	v_pk_add_f32 v[48:49], v[48:49], v[144:145]
	v_pk_add_f32 v[60:61], v[60:61], v[146:147]
	v_pk_mul_f32 v[52:53], v[52:53], v[64:65]
	v_pk_add_f32 v[48:49], v[48:49], v[60:61]
	v_lshl_add_u64 v[56:57], v[56:57], 0, v[136:137]
	v_add_f32_e32 v48, v48, v49
	v_fmamk_f32 v48, v48, 0x3b000000, v218
	v_rsq_f32_e32 v232, v48
	v_cvt_pk_bf16_f32 v48, v52, v53
	v_cvt_pk_bf16_f32 v49, v54, v55
	v_cvt_pk_bf16_f32 v50, v50, v51
	v_cvt_pk_bf16_f32 v51, v58, v59
	global_store_dwordx4 v[56:57], v[48:51], off
	s_nop 1
	v_add_u32_e32 v50, 0x90, v204
	v_mov_b32_e32 v48, v232
	v_mov_b64_e32 v[52:53], s[30:31]
	v_mad_i64_i32 v[52:53], s[0:1], v50, s55, v[52:53]
	v_lshl_add_u64 v[52:53], s[36:37], 1, v[52:53]
	v_lshl_add_u64 v[52:53], v[52:53], 0, v[136:137]
	v_pk_mul_f32 v[46:47], v[46:47], v[48:49] op_sel_hi:[1,0]
	v_pk_mul_f32 v[44:45], v[44:45], v[48:49] op_sel_hi:[1,0]
	v_pk_mul_f32 v[54:55], v[42:43], v[48:49] op_sel_hi:[1,0]
	v_pk_mul_f32 v[42:43], v[40:41], v[48:49] op_sel_hi:[1,0]
	v_cvt_pk_bf16_f32 v40, v44, v45
	v_cvt_pk_bf16_f32 v41, v46, v47
	s_and_b64 vcc, exec, s[6:7]
	s_mov_b64 s[0:1], -1
	v_cvt_pk_bf16_f32 v42, v42, v43
	v_cvt_pk_bf16_f32 v43, v54, v55
	global_store_dwordx4 v[52:53], v[40:43], off
	s_cbranch_vccnz .LBB0_921
	s_nop 0
	v_mad_i64_i32 v[40:41], s[0:1], v50, s55, 0
	v_readlane_b32 s0, v254, 25
	v_readlane_b32 s1, v254, 26
	s_nop 1
	v_lshl_add_u64 v[40:41], s[0:1], 0, v[40:41]
	v_lshl_add_u64 v[40:41], s[28:29], 1, v[40:41]
	v_lshl_add_u64 v[40:41], v[40:41], 0, s[16:17]
	s_mov_b64 s[0:1], 0

.LBB0_923:
	v_mov_b32_e32 v49, v48
	v_mov_b32_e32 v42, v48
	v_mov_b32_e32 v43, v48
	v_pk_mul_f32 v[38:39], v[38:39], v[42:43]
	v_pk_mul_f32 v[42:43], v[34:35], v[42:43]
	v_pk_mul_f32 v[34:35], v[32:33], v[48:49]
	v_mov_b32_e32 v32, v132
	v_mov_b32_e32 v33, v124
	v_mov_b32_e32 v124, v133
	v_mov_b32_e32 v44, v134
	v_mov_b32_e32 v45, v126
	v_mov_b32_e32 v126, v135
	v_pk_add_f32 v[32:33], v[32:33], v[124:125]
	v_pk_add_f32 v[44:45], v[44:45], v[126:127]
	v_pk_mul_f32 v[36:37], v[36:37], v[48:49]
	v_pk_add_f32 v[32:33], v[32:33], v[44:45]
	v_lshl_add_u64 v[40:41], v[40:41], 0, v[136:137]
	v_add_f32_e32 v32, v32, v33
	v_fmamk_f32 v32, v32, 0x3b000000, v218
	v_rsq_f32_e32 v232, v32
	v_cvt_pk_bf16_f32 v32, v36, v37
	v_cvt_pk_bf16_f32 v33, v38, v39
	v_cvt_pk_bf16_f32 v34, v34, v35
	v_cvt_pk_bf16_f32 v35, v42, v43
	global_store_dwordx4 v[40:41], v[32:35], off
	s_nop 1
	v_add_u32_e32 v34, 0xa0, v204
	v_mov_b32_e32 v32, v232
	v_mov_b64_e32 v[36:37], s[30:31]
	v_mad_i64_i32 v[36:37], s[0:1], v34, s55, v[36:37]
	v_lshl_add_u64 v[36:37], s[36:37], 1, v[36:37]
	v_lshl_add_u64 v[36:37], v[36:37], 0, v[136:137]
	v_pk_mul_f32 v[30:31], v[30:31], v[32:33] op_sel_hi:[1,0]
	v_pk_mul_f32 v[28:29], v[28:29], v[32:33] op_sel_hi:[1,0]
	v_pk_mul_f32 v[38:39], v[26:27], v[32:33] op_sel_hi:[1,0]
	v_pk_mul_f32 v[26:27], v[24:25], v[32:33] op_sel_hi:[1,0]
	v_cvt_pk_bf16_f32 v24, v28, v29
	v_cvt_pk_bf16_f32 v25, v30, v31
	s_and_b64 vcc, exec, s[6:7]
	s_mov_b64 s[0:1], -1
	v_cvt_pk_bf16_f32 v26, v26, v27
	v_cvt_pk_bf16_f32 v27, v38, v39
	global_store_dwordx4 v[36:37], v[24:27], off
	s_cbranch_vccnz .LBB0_925
	s_nop 0
	v_mad_i64_i32 v[24:25], s[0:1], v34, s55, 0
	v_readlane_b32 s0, v254, 25
	v_readlane_b32 s1, v254, 26
	s_nop 1
	v_lshl_add_u64 v[24:25], s[0:1], 0, v[24:25]
	v_lshl_add_u64 v[24:25], s[28:29], 1, v[24:25]
	v_lshl_add_u64 v[24:25], v[24:25], 0, s[16:17]
	s_mov_b64 s[0:1], 0

.LBB0_927:
	v_mov_b32_e32 v33, v32
	v_mov_b32_e32 v26, v32
	v_mov_b32_e32 v27, v32
	v_pk_mul_f32 v[22:23], v[22:23], v[26:27]
	v_pk_mul_f32 v[26:27], v[18:19], v[26:27]
	v_pk_mul_f32 v[18:19], v[16:17], v[32:33]
	v_mov_b32_e32 v16, v108
	v_mov_b32_e32 v17, v104
	v_mov_b32_e32 v104, v109
	v_mov_b32_e32 v28, v110
	v_mov_b32_e32 v29, v106
	v_mov_b32_e32 v106, v111
	v_pk_add_f32 v[16:17], v[16:17], v[104:105]
	v_pk_add_f32 v[28:29], v[28:29], v[106:107]
	v_pk_mul_f32 v[20:21], v[20:21], v[32:33]
	v_pk_add_f32 v[16:17], v[16:17], v[28:29]
	v_lshl_add_u64 v[24:25], v[24:25], 0, v[136:137]
	v_add_f32_e32 v16, v16, v17
	v_fmamk_f32 v16, v16, 0x3b000000, v218
	v_rsq_f32_e32 v232, v16
	v_cvt_pk_bf16_f32 v16, v20, v21
	v_cvt_pk_bf16_f32 v17, v22, v23
	v_cvt_pk_bf16_f32 v18, v18, v19
	v_cvt_pk_bf16_f32 v19, v26, v27
	global_store_dwordx4 v[24:25], v[16:19], off
	s_nop 1
	v_add_u32_e32 v18, 0xb0, v204
	v_mov_b32_e32 v16, v232
	v_mov_b64_e32 v[20:21], s[30:31]
	v_mad_i64_i32 v[20:21], s[0:1], v18, s55, v[20:21]
	v_lshl_add_u64 v[20:21], s[36:37], 1, v[20:21]
	v_lshl_add_u64 v[20:21], v[20:21], 0, v[136:137]
	v_pk_mul_f32 v[14:15], v[14:15], v[16:17] op_sel_hi:[1,0]
	v_pk_mul_f32 v[12:13], v[12:13], v[16:17] op_sel_hi:[1,0]
	v_pk_mul_f32 v[22:23], v[10:11], v[16:17] op_sel_hi:[1,0]
	v_pk_mul_f32 v[10:11], v[8:9], v[16:17] op_sel_hi:[1,0]
	v_cvt_pk_bf16_f32 v8, v12, v13
	v_cvt_pk_bf16_f32 v9, v14, v15
	s_and_b64 vcc, exec, s[6:7]
	s_mov_b64 s[0:1], -1
	v_cvt_pk_bf16_f32 v10, v10, v11
	v_cvt_pk_bf16_f32 v11, v22, v23
	global_store_dwordx4 v[20:21], v[8:11], off
	s_cbranch_vccnz .LBB0_929
	s_nop 0
	v_mad_i64_i32 v[8:9], s[0:1], v18, s55, 0
	v_readlane_b32 s0, v254, 25
	v_readlane_b32 s1, v254, 26
	s_nop 1
	v_lshl_add_u64 v[8:9], s[0:1], 0, v[8:9]
	v_lshl_add_u64 v[8:9], s[28:29], 1, v[8:9]
	v_lshl_add_u64 v[8:9], v[8:9], 0, s[16:17]
	s_mov_b64 s[0:1], 0

.LBB0_1367:
	v_mov_b32_e32 v128, v173
	v_mov_b32_e32 v129, v172
	s_lshl_b32 s0, s0, 8
	s_add_i32 s0, s0, s35
	v_lshlrev_b32_e32 v144, 3, v128
	v_add_u32_e32 v181, s0, v129
	v_ashrrev_i32_e32 v145, 31, v144
	v_lshlrev_b32_e32 v160, 5, v181
	v_lshl_add_u64 v[182:183], v[144:145], 2, s[76:77]
	v_lshl_add_u64 v[132:133], v[160:161], 2, v[182:183]
	v_add_u32_e32 v136, 0x200, v160
	v_mov_b32_e32 v137, v161
	global_load_dwordx4 v[128:131], v[132:133], off
	s_nop 0
	global_load_dwordx4 v[132:135], v[132:133], off offset:16
	v_lshl_add_u64 v[140:141], v[136:137], 2, v[182:183]
	global_load_dwordx4 v[136:139], v[140:141], off
	s_nop 0
	global_load_dwordx4 v[140:143], v[140:141], off offset:16
	v_and_b32_e32 v148, 64, v178
	s_lshl_b32 s0, s1, 7
	v_xor_b32_e32 v146, 16, v178
	v_add_u32_e32 v148, 64, v148
	s_or_b32 s0, s0, s36
	v_cmp_lt_i32_e32 vcc, v146, v148
	v_mov_b32_e32 v145, v161
	v_add_u32_e32 v170, s0, v144
	v_cndmask_b32_e32 v146, v178, v146, vcc
	v_add_u32_e32 v144, 0x400, v160
	v_mov_b32_e32 v147, v161
	v_mov_b32_e32 v187, v161
	v_lshlrev_b32_e32 v171, 2, v146
	v_add_u32_e32 v146, 0x600, v160
	v_add_u32_e32 v186, 0x1400, v160
	v_lshl_add_u64 v[144:145], v[144:145], 2, v[182:183]
	v_lshl_add_u64 v[146:147], v[146:147], 2, v[182:183]
	v_lshl_add_u64 v[212:213], v[186:187], 2, v[182:183]
	global_load_dwordx4 v[186:189], v[144:145], off
	global_load_dwordx4 v[190:193], v[144:145], off offset:16
	global_load_dwordx4 v[194:197], v[146:147], off
	global_load_dwordx4 v[198:201], v[146:147], off offset:16
	v_xor_b32_e32 v150, 32, v178
	v_cmp_lt_i32_e32 vcc, v150, v148
	v_mov_b32_e32 v149, v161
	v_mov_b32_e32 v151, v161
	v_cndmask_b32_e32 v148, v178, v150, vcc
	v_lshlrev_b32_e32 v185, 2, v148
	v_add_u32_e32 v148, 0x1000, v160
	v_add_u32_e32 v150, 0x1200, v160
	v_add_u32_e32 v160, 0x1600, v160
	v_lshl_add_u64 v[148:149], v[148:149], 2, v[182:183]
	v_lshl_add_u64 v[210:211], v[150:151], 2, v[182:183]
	global_load_dwordx4 v[220:223], v[148:149], off
	global_load_dwordx4 v[224:227], v[148:149], off offset:16
	global_load_dwordx4 v[228:231], v[210:211], off
	global_load_dwordx4 v[232:235], v[210:211], off offset:16
	global_load_dwordx4 v[236:239], v[212:213], off
	global_load_dwordx4 v[240:243], v[212:213], off offset:16
	v_lshl_add_u64 v[252:253], v[160:161], 2, v[182:183]
	global_load_dwordx4 v[244:247], v[252:253], off
	global_load_dwordx4 v[248:251], v[252:253], off offset:16
	v_pk_mul_f32 v[122:123], v[126:127], v[122:123]
	v_pk_mul_f32 v[120:121], v[124:125], v[120:121]
	v_pk_mul_f32 v[112:113], v[116:117], v[112:113]
	v_pk_mul_f32 v[114:115], v[118:119], v[114:115]
	v_pk_mul_f32 v[106:107], v[110:111], v[106:107]
	v_pk_mul_f32 v[104:105], v[108:109], v[104:105]
	v_pk_mul_f32 v[98:99], v[102:103], v[98:99]
	v_pk_mul_f32 v[96:97], v[100:101], v[96:97]
	v_pk_mul_f32 v[90:91], v[94:95], v[90:91]
	v_pk_mul_f32 v[88:89], v[92:93], v[88:89]
	v_pk_mul_f32 v[82:83], v[86:87], v[82:83]
	v_pk_mul_f32 v[80:81], v[84:85], v[80:81]
	v_pk_mul_f32 v[74:75], v[78:79], v[74:75]
	v_pk_mul_f32 v[72:73], v[76:77], v[72:73]
	v_pk_mul_f32 v[66:67], v[70:71], v[66:67]
	v_pk_mul_f32 v[64:65], v[68:69], v[64:65]
	v_pk_mul_f32 v[58:59], v[62:63], v[58:59]
	v_pk_mul_f32 v[56:57], v[60:61], v[56:57]
	v_pk_mul_f32 v[50:51], v[54:55], v[50:51]
	v_pk_mul_f32 v[48:49], v[52:53], v[48:49]
	v_pk_mul_f32 v[42:43], v[46:47], v[42:43]
	v_pk_mul_f32 v[40:41], v[44:45], v[40:41]
	v_pk_mul_f32 v[34:35], v[38:39], v[34:35]
	v_pk_mul_f32 v[32:33], v[36:37], v[32:33]
	v_pk_mul_f32 v[26:27], v[30:31], v[26:27]
	v_pk_mul_f32 v[24:25], v[28:29], v[24:25]
	v_pk_mul_f32 v[18:19], v[22:23], v[18:19]
	v_pk_mul_f32 v[16:17], v[20:21], v[16:17]
	v_pk_mul_f32 v[10:11], v[14:15], v[10:11]
	v_pk_mul_f32 v[8:9], v[12:13], v[8:9]
	v_pk_mul_f32 v[2:3], v[6:7], v[2:3]
	v_pk_mul_f32 v[0:1], v[4:5], v[0:1]
	s_waitcnt vmcnt(0)
	v_mov_b32_e32 v144, v128
	v_mov_b32_e32 v145, v132
	v_mov_b32_e32 v132, v129
	v_mov_b32_e32 v128, v130
	v_mov_b32_e32 v129, v134
	v_mov_b32_e32 v134, v131
	v_mov_b32_e32 v130, v136
	v_mov_b32_e32 v131, v140
	v_mov_b32_e32 v140, v137
	v_mov_b32_e32 v136, v138
	v_mov_b32_e32 v137, v142
	v_mov_b32_e32 v142, v139
	v_pk_add_f32 v[132:133], v[144:145], v[132:133]
	v_pk_add_f32 v[128:129], v[128:129], v[134:135]
	v_pk_add_f32 v[130:131], v[130:131], v[140:141]
	v_pk_add_f32 v[134:135], v[136:137], v[142:143]
	v_pk_add_f32 v[128:129], v[132:133], v[128:129]
	v_pk_add_f32 v[130:131], v[130:131], v[134:135]
	v_add_f32_e32 v128, v128, v129
	v_add_f32_e32 v129, v130, v131
	ds_bpermute_b32 v130, v171, v128
	ds_bpermute_b32 v131, v171, v129
	s_nop 0
	s_waitcnt lgkmcnt(1)
	v_add_f32_e32 v130, v128, v130
	ds_bpermute_b32 v132, v185, v130
	s_waitcnt lgkmcnt(1)
	v_add_f32_e32 v131, v129, v131
	ds_bpermute_b32 v133, v185, v131
	s_waitcnt lgkmcnt(1)
	v_add_f32_e32 v130, v130, v132
	v_fmamk_f32 v130, v130, 0x3a000000, v179
	v_rsq_f32_e32 v202, v130
	s_waitcnt lgkmcnt(0)
	v_add_f32_e32 v131, v131, v133
	v_fmamk_f32 v131, v131, 0x3a000000, v179
	v_rsq_f32_e32 v203, v131
	v_mov_b32_e32 v182, v186
	v_mov_b32_e32 v183, v190
	v_mov_b32_e32 v190, v187
	v_mov_b32_e32 v186, v188
	v_mov_b32_e32 v187, v192
	v_mov_b32_e32 v192, v189
	v_pk_add_f32 v[182:183], v[182:183], v[190:191]
	v_pk_add_f32 v[186:187], v[186:187], v[192:193]
	v_pk_add_f32 v[182:183], v[182:183], v[186:187]
	v_add_f32_e32 v182, v182, v183
	ds_bpermute_b32 v183, v171, v182
	v_mov_b32_e32 v160, v202
	s_waitcnt lgkmcnt(0)
	v_add_f32_e32 v182, v182, v183
	ds_bpermute_b32 v183, v185, v182
	s_waitcnt lgkmcnt(0)
	v_add_f32_e32 v182, v182, v183
	v_fmamk_f32 v182, v182, 0x3a000000, v179
	v_rsq_f32_e32 v204, v182
	v_mov_b32_e32 v186, v196
	v_mov_b32_e32 v187, v200
	v_mov_b32_e32 v182, v194
	v_mov_b32_e32 v183, v198
	v_mov_b32_e32 v198, v195
	v_mov_b32_e32 v200, v197
	v_pk_add_f32 v[182:183], v[182:183], v[198:199]
	v_pk_add_f32 v[186:187], v[186:187], v[200:201]
	v_pk_add_f32 v[182:183], v[182:183], v[186:187]
	v_add_f32_e32 v182, v182, v183
	ds_bpermute_b32 v183, v171, v182
	v_mov_b32_e32 v188, v203
	s_waitcnt lgkmcnt(0)
	v_add_f32_e32 v182, v182, v183
	ds_bpermute_b32 v183, v185, v182
	s_waitcnt lgkmcnt(0)
	v_add_f32_e32 v182, v182, v183
	v_fmamk_f32 v182, v182, 0x3a000000, v179
	v_rsq_f32_e32 v205, v182
	s_waitcnt vmcnt(7)
	v_mov_b32_e32 v186, v222
	s_waitcnt vmcnt(6)
	v_mov_b32_e32 v187, v226
	v_mov_b32_e32 v182, v220
	v_mov_b32_e32 v183, v224
	v_mov_b32_e32 v224, v221
	v_mov_b32_e32 v226, v223
	v_pk_add_f32 v[182:183], v[182:183], v[224:225]
	v_pk_add_f32 v[186:187], v[186:187], v[226:227]
	v_pk_add_f32 v[182:183], v[182:183], v[186:187]
	v_add_f32_e32 v182, v182, v183
	ds_bpermute_b32 v183, v171, v182
	s_waitcnt lgkmcnt(0)
	v_add_f32_e32 v182, v182, v183
	ds_bpermute_b32 v183, v185, v182
	v_mov_b32_e32 v186, v204
	s_waitcnt lgkmcnt(0)
	v_add_f32_e32 v182, v182, v183
	v_fmamk_f32 v182, v182, 0x3a000000, v179
	v_rsq_f32_e32 v206, v182
	s_waitcnt vmcnt(5)
	v_mov_b32_e32 v182, v228
	s_waitcnt vmcnt(4)
	v_mov_b32_e32 v183, v232
	v_mov_b32_e32 v232, v229
	v_mov_b32_e32 v228, v230
	v_mov_b32_e32 v229, v234
	v_mov_b32_e32 v234, v231
	v_pk_add_f32 v[232:233], v[182:183], v[232:233]
	v_pk_add_f32 v[234:235], v[228:229], v[234:235]
	v_pk_add_f32 v[232:233], v[232:233], v[234:235]
	v_add_f32_e32 v232, v232, v233
	ds_bpermute_b32 v233, v171, v232
	s_waitcnt lgkmcnt(0)
	v_add_f32_e32 v232, v232, v233
	ds_bpermute_b32 v233, v185, v232
	s_waitcnt lgkmcnt(0)
	v_add_f32_e32 v232, v232, v233
	v_fmamk_f32 v232, v232, 0x3a000000, v179
	v_rsq_f32_e32 v207, v232
	v_mov_b32_e32 v234, v205
	s_waitcnt vmcnt(3)
	v_mov_b32_e32 v232, v236
	s_waitcnt vmcnt(2)
	v_mov_b32_e32 v233, v240
	v_mov_b32_e32 v240, v237
	v_mov_b32_e32 v236, v238
	v_mov_b32_e32 v237, v242
	v_mov_b32_e32 v242, v239
	v_pk_add_f32 v[240:241], v[232:233], v[240:241]
	v_pk_add_f32 v[242:243], v[236:237], v[242:243]
	v_pk_add_f32 v[240:241], v[240:241], v[242:243]
	v_add_f32_e32 v240, v240, v241
	ds_bpermute_b32 v241, v171, v240
	s_waitcnt lgkmcnt(0)
	v_add_f32_e32 v240, v240, v241
	ds_bpermute_b32 v241, v185, v240
	s_waitcnt lgkmcnt(0)
	v_add_f32_e32 v240, v240, v241
	v_fmamk_f32 v240, v240, 0x3a000000, v179
	v_rsq_f32_e32 v208, v240
	v_mov_b32_e32 v242, v206
	s_waitcnt vmcnt(1)
	v_mov_b32_e32 v240, v244
	s_waitcnt vmcnt(0)
	v_mov_b32_e32 v241, v248
	v_mov_b32_e32 v248, v245
	v_mov_b32_e32 v244, v246
	v_mov_b32_e32 v245, v250
	v_mov_b32_e32 v250, v247
	v_pk_add_f32 v[248:249], v[240:241], v[248:249]
	v_pk_add_f32 v[250:251], v[244:245], v[250:251]
	v_pk_add_f32 v[248:249], v[248:249], v[250:251]
	v_add_f32_e32 v248, v248, v249
	ds_bpermute_b32 v249, v171, v248
	v_mov_b32_e32 v251, v207
	s_waitcnt lgkmcnt(0)
	v_add_f32_e32 v248, v248, v249
	ds_bpermute_b32 v249, v185, v248
	s_waitcnt lgkmcnt(0)
	v_add_f32_e32 v248, v248, v249
	v_fmamk_f32 v248, v248, 0x3a000000, v179
	v_rsq_f32_e32 v209, v248
	v_mov_b32_e32 v243, v208
	v_ashrrev_i32_e32 v171, 31, v170
	v_mul_f32_e32 v250, 0xbfb8aa3b, v160
	v_pk_mul_f32 v[240:241], v[124:125], v[250:251] op_sel_hi:[1,0]
	v_mov_b32_e32 v248, v209
	v_exp_f32_e32 v249, v240
	v_pk_mul_f32 v[246:247], v[126:127], v[250:251] op_sel_hi:[1,0]
	v_exp_f32_e32 v245, v241
	v_exp_f32_e32 v240, v246
	v_exp_f32_e32 v241, v247
	v_add_f32_e32 v249, 1.0, v249
	v_rcp_f32_e32 v246, v249
	v_add_f32_e32 v249, 1.0, v245
	v_rcp_f32_e32 v247, v249
	v_add_f32_e32 v249, 1.0, v240
	v_pk_mul_f32 v[126:127], v[116:117], v[250:251] op_sel_hi:[1,0]
	v_rcp_f32_e32 v240, v249
	v_add_f32_e32 v249, 1.0, v241
	v_pk_mul_f32 v[124:125], v[118:119], v[250:251] op_sel_hi:[1,0]
	v_exp_f32_e32 v126, v126
	v_exp_f32_e32 v127, v127
	v_rcp_f32_e32 v241, v249
	v_exp_f32_e32 v249, v124
	v_exp_f32_e32 v250, v125
	v_add_f32_e32 v124, 1.0, v126
	v_add_f32_e32 v125, 1.0, v127
	v_rcp_f32_e32 v124, v124
	v_rcp_f32_e32 v125, v125
	v_add_f32_e32 v126, 1.0, v249
	v_add_f32_e32 v127, 1.0, v250
	v_rcp_f32_e32 v126, v126
	v_rcp_f32_e32 v127, v127
	v_mul_f32_e32 v244, v160, v160
	v_pk_mul_f32 v[112:113], v[112:113], v[244:245] op_sel_hi:[1,0]
	v_pk_mul_f32 v[120:121], v[120:121], v[244:245] op_sel_hi:[1,0]
	v_pk_mul_f32 v[122:123], v[122:123], v[244:245] op_sel_hi:[1,0]
	v_pk_mul_f32 v[114:115], v[114:115], v[244:245] op_sel_hi:[1,0]
	v_pk_mul_f32 v[112:113], v[112:113], v[124:125]
	v_pk_mul_f32 v[122:123], v[122:123], v[240:241]
	v_pk_mul_f32 v[120:121], v[120:121], v[246:247]
	v_pk_mul_f32 v[114:115], v[114:115], v[126:127]
	v_cvt_pk_bf16_f32 v116, v120, v121
	v_cvt_pk_bf16_f32 v117, v122, v123
	v_cvt_pk_bf16_f32 v118, v112, v113
	v_mov_b64_e32 v[112:113], s[68:69]
	v_cvt_pk_bf16_f32 v119, v114, v115
	v_mad_i64_i32 v[120:121], s[0:1], v181, s44, v[112:113]
	v_lshlrev_b64 v[114:115], 1, v[170:171]
	v_lshl_add_u64 v[120:121], v[120:121], 0, v[114:115]
	global_store_dwordx4 v[120:121], v[116:119], off
	s_andn2_b64 vcc, exec, s[4:5]
	s_nop 0
	v_mul_f32_e32 v116, 0xbfb8aa3b, v188
	v_pk_mul_f32 v[122:123], v[108:109], v[116:117] op_sel_hi:[1,0]
	v_pk_mul_f32 v[120:121], v[110:111], v[116:117] op_sel_hi:[1,0]
	v_exp_f32_e32 v117, v122
	v_exp_f32_e32 v119, v123
	v_exp_f32_e32 v122, v120
	v_exp_f32_e32 v123, v121
	v_add_f32_e32 v117, 1.0, v117
	v_rcp_f32_e32 v120, v117
	v_add_f32_e32 v117, 1.0, v119
	v_rcp_f32_e32 v121, v117
	v_add_f32_e32 v117, 1.0, v122
	v_rcp_f32_e32 v122, v117
	v_add_f32_e32 v117, 1.0, v123
	v_pk_mul_f32 v[108:109], v[102:103], v[116:117] op_sel_hi:[1,0]
	v_pk_mul_f32 v[110:111], v[100:101], v[116:117] op_sel_hi:[1,0]
	v_rcp_f32_e32 v123, v117
	v_exp_f32_e32 v110, v110
	v_exp_f32_e32 v111, v111
	v_exp_f32_e32 v116, v108
	v_exp_f32_e32 v117, v109
	v_add_f32_e32 v108, 1.0, v110
	v_add_f32_e32 v109, 1.0, v111
	v_add_f32_e32 v110, 1.0, v116
	v_add_f32_e32 v111, 1.0, v117
	v_rcp_f32_e32 v108, v108
	v_rcp_f32_e32 v109, v109
	v_rcp_f32_e32 v110, v110
	v_rcp_f32_e32 v111, v111
	v_mul_f32_e32 v118, v188, v188
	v_pk_mul_f32 v[96:97], v[96:97], v[118:119] op_sel_hi:[1,0]
	v_pk_mul_f32 v[98:99], v[98:99], v[118:119] op_sel_hi:[1,0]
	v_pk_mul_f32 v[104:105], v[104:105], v[118:119] op_sel_hi:[1,0]
	v_pk_mul_f32 v[106:107], v[106:107], v[118:119] op_sel_hi:[1,0]
	v_pk_mul_f32 v[100:101], v[98:99], v[110:111]
	v_pk_mul_f32 v[98:99], v[96:97], v[108:109]
	v_add_u32_e32 v102, 16, v181
	v_pk_mul_f32 v[106:107], v[106:107], v[122:123]
	v_pk_mul_f32 v[104:105], v[104:105], v[120:121]
	s_nop 0
	v_cvt_pk_bf16_f32 v96, v104, v105
	v_cvt_pk_bf16_f32 v97, v106, v107
	v_cvt_pk_bf16_f32 v98, v98, v99
	v_cvt_pk_bf16_f32 v99, v100, v101
	v_mad_i64_i32 v[100:101], s[0:1], v102, s44, v[112:113]
	v_lshl_add_u64 v[100:101], v[100:101], 0, v[114:115]
	global_store_dwordx4 v[100:101], v[96:99], off
	s_nop 1
	v_mul_f32_e32 v96, 0xbfb8aa3b, v186
	v_pk_mul_f32 v[102:103], v[92:93], v[96:97] op_sel_hi:[1,0]
	v_pk_mul_f32 v[100:101], v[94:95], v[96:97] op_sel_hi:[1,0]
	v_exp_f32_e32 v97, v102
	v_exp_f32_e32 v99, v103
	v_exp_f32_e32 v102, v100
	v_exp_f32_e32 v103, v101
	v_add_f32_e32 v97, 1.0, v97
	v_rcp_f32_e32 v100, v97
	v_add_f32_e32 v97, 1.0, v99
	v_rcp_f32_e32 v101, v97
	v_add_f32_e32 v97, 1.0, v102
	v_rcp_f32_e32 v102, v97
	v_add_f32_e32 v97, 1.0, v103
	v_pk_mul_f32 v[92:93], v[86:87], v[96:97] op_sel_hi:[1,0]
	v_pk_mul_f32 v[94:95], v[84:85], v[96:97] op_sel_hi:[1,0]
	v_rcp_f32_e32 v103, v97
	v_exp_f32_e32 v94, v94
	v_exp_f32_e32 v95, v95
	v_exp_f32_e32 v96, v92
	v_exp_f32_e32 v97, v93
	v_add_f32_e32 v92, 1.0, v94
	v_add_f32_e32 v93, 1.0, v95
	v_add_f32_e32 v94, 1.0, v96
	v_add_f32_e32 v95, 1.0, v97
	v_rcp_f32_e32 v92, v92
	v_rcp_f32_e32 v93, v93
	v_rcp_f32_e32 v94, v94
	v_rcp_f32_e32 v95, v95
	v_mul_f32_e32 v98, v186, v186
	v_pk_mul_f32 v[80:81], v[80:81], v[98:99] op_sel_hi:[1,0]
	v_pk_mul_f32 v[82:83], v[82:83], v[98:99] op_sel_hi:[1,0]
	v_pk_mul_f32 v[88:89], v[88:89], v[98:99] op_sel_hi:[1,0]
	v_pk_mul_f32 v[90:91], v[90:91], v[98:99] op_sel_hi:[1,0]
	v_pk_mul_f32 v[84:85], v[82:83], v[94:95]
	v_pk_mul_f32 v[82:83], v[80:81], v[92:93]
	v_add_u32_e32 v86, 32, v181
	v_pk_mul_f32 v[90:91], v[90:91], v[102:103]
	v_pk_mul_f32 v[88:89], v[88:89], v[100:101]
	s_nop 0
	v_cvt_pk_bf16_f32 v80, v88, v89
	v_cvt_pk_bf16_f32 v81, v90, v91
	v_cvt_pk_bf16_f32 v82, v82, v83
	v_cvt_pk_bf16_f32 v83, v84, v85
	v_mad_i64_i32 v[84:85], s[0:1], v86, s44, v[112:113]
	v_lshl_add_u64 v[84:85], v[84:85], 0, v[114:115]
	global_store_dwordx4 v[84:85], v[80:83], off
	s_nop 1
	v_mul_f32_e32 v80, 0xbfb8aa3b, v234
	v_pk_mul_f32 v[86:87], v[76:77], v[80:81] op_sel_hi:[1,0]
	v_pk_mul_f32 v[84:85], v[78:79], v[80:81] op_sel_hi:[1,0]
	v_exp_f32_e32 v81, v86
	v_exp_f32_e32 v83, v87
	v_exp_f32_e32 v86, v84
	v_exp_f32_e32 v87, v85
	v_add_f32_e32 v81, 1.0, v81
	v_rcp_f32_e32 v84, v81
	v_add_f32_e32 v81, 1.0, v83
	v_rcp_f32_e32 v85, v81
	v_add_f32_e32 v81, 1.0, v86
	v_rcp_f32_e32 v86, v81
	v_add_f32_e32 v81, 1.0, v87
	v_pk_mul_f32 v[76:77], v[70:71], v[80:81] op_sel_hi:[1,0]
	v_pk_mul_f32 v[78:79], v[68:69], v[80:81] op_sel_hi:[1,0]
	v_rcp_f32_e32 v87, v81
	v_exp_f32_e32 v78, v78
	v_exp_f32_e32 v79, v79
	v_exp_f32_e32 v80, v76
	v_exp_f32_e32 v81, v77
	v_add_f32_e32 v76, 1.0, v78
	v_add_f32_e32 v77, 1.0, v79
	v_add_f32_e32 v78, 1.0, v80
	v_add_f32_e32 v79, 1.0, v81
	v_rcp_f32_e32 v76, v76
	v_rcp_f32_e32 v77, v77
	v_rcp_f32_e32 v78, v78
	v_rcp_f32_e32 v79, v79
	v_mul_f32_e32 v82, v234, v234
	v_pk_mul_f32 v[64:65], v[64:65], v[82:83] op_sel_hi:[1,0]
	v_pk_mul_f32 v[66:67], v[66:67], v[82:83] op_sel_hi:[1,0]
	v_pk_mul_f32 v[72:73], v[72:73], v[82:83] op_sel_hi:[1,0]
	v_pk_mul_f32 v[74:75], v[74:75], v[82:83] op_sel_hi:[1,0]
	v_pk_mul_f32 v[68:69], v[66:67], v[78:79]
	v_pk_mul_f32 v[66:67], v[64:65], v[76:77]
	v_add_u32_e32 v70, 48, v181
	v_pk_mul_f32 v[74:75], v[74:75], v[86:87]
	v_pk_mul_f32 v[72:73], v[72:73], v[84:85]
	s_nop 0
	v_cvt_pk_bf16_f32 v64, v72, v73
	v_cvt_pk_bf16_f32 v65, v74, v75
	v_cvt_pk_bf16_f32 v66, v66, v67
	v_cvt_pk_bf16_f32 v67, v68, v69
	v_mad_i64_i32 v[68:69], s[0:1], v70, s44, v[112:113]
	v_lshl_add_u64 v[68:69], v[68:69], 0, v[114:115]
	global_store_dwordx4 v[68:69], v[64:67], off
	s_nop 1
	v_add_u32_e32 v65, 0x80, v181
	v_mul_f32_e32 v64, 0xbfb8aa3b, v242
	v_pk_mul_f32 v[70:71], v[60:61], v[64:65] op_sel_hi:[1,0]
	v_pk_mul_f32 v[68:69], v[62:63], v[64:65] op_sel_hi:[1,0]
	v_exp_f32_e32 v67, v70
	v_exp_f32_e32 v70, v71
	v_exp_f32_e32 v71, v68
	v_exp_f32_e32 v72, v69
	v_add_f32_e32 v67, 1.0, v67
	v_rcp_f32_e32 v68, v67
	v_add_f32_e32 v67, 1.0, v70
	v_rcp_f32_e32 v69, v67
	v_add_f32_e32 v67, 1.0, v71
	v_mul_f32_e32 v66, v242, v242
	v_rcp_f32_e32 v70, v67
	v_add_f32_e32 v67, 1.0, v72
	v_pk_mul_f32 v[60:61], v[54:55], v[64:65] op_sel_hi:[1,0]
	v_pk_mul_f32 v[62:63], v[52:53], v[64:65] op_sel_hi:[1,0]
	v_rcp_f32_e32 v71, v67
	v_pk_mul_f32 v[56:57], v[56:57], v[66:67] op_sel_hi:[1,0]
	v_pk_mul_f32 v[58:59], v[58:59], v[66:67] op_sel_hi:[1,0]
	v_exp_f32_e32 v62, v62
	v_exp_f32_e32 v63, v63
	v_exp_f32_e32 v64, v60
	v_exp_f32_e32 v67, v61
	v_add_f32_e32 v60, 1.0, v62
	v_add_f32_e32 v61, 1.0, v63
	v_add_f32_e32 v62, 1.0, v64
	v_add_f32_e32 v63, 1.0, v67
	v_rcp_f32_e32 v60, v60
	v_rcp_f32_e32 v61, v61
	v_rcp_f32_e32 v62, v62
	v_rcp_f32_e32 v63, v63
	v_pk_mul_f32 v[48:49], v[48:49], v[66:67] op_sel_hi:[1,0]
	v_pk_mul_f32 v[50:51], v[50:51], v[66:67] op_sel_hi:[1,0]
	v_pk_mul_f32 v[58:59], v[58:59], v[70:71]
	v_pk_mul_f32 v[52:53], v[50:51], v[62:63]
	v_pk_mul_f32 v[50:51], v[48:49], v[60:61]
	v_pk_mul_f32 v[56:57], v[56:57], v[68:69]
	s_nop 0
	v_cvt_pk_bf16_f32 v48, v56, v57
	v_cvt_pk_bf16_f32 v49, v58, v59
	v_cvt_pk_bf16_f32 v50, v50, v51
	v_cvt_pk_bf16_f32 v51, v52, v53
	v_mad_i64_i32 v[52:53], s[0:1], v65, s44, v[112:113]
	v_lshl_add_u64 v[52:53], v[52:53], 0, v[114:115]
	global_store_dwordx4 v[52:53], v[48:51], off
	s_nop 1
	v_mul_f32_e32 v48, 0xbfb8aa3b, v251
	v_pk_mul_f32 v[54:55], v[44:45], v[48:49] op_sel_hi:[1,0]
	v_pk_mul_f32 v[52:53], v[46:47], v[48:49] op_sel_hi:[1,0]
	v_exp_f32_e32 v49, v54
	v_exp_f32_e32 v51, v55
	v_exp_f32_e32 v54, v52
	v_exp_f32_e32 v55, v53
	v_add_f32_e32 v49, 1.0, v49
	v_rcp_f32_e32 v52, v49
	v_add_f32_e32 v49, 1.0, v51
	v_rcp_f32_e32 v53, v49
	v_add_f32_e32 v49, 1.0, v54
	v_rcp_f32_e32 v54, v49
	v_add_f32_e32 v49, 1.0, v55
	v_pk_mul_f32 v[44:45], v[38:39], v[48:49] op_sel_hi:[1,0]
	v_pk_mul_f32 v[46:47], v[36:37], v[48:49] op_sel_hi:[1,0]
	v_rcp_f32_e32 v55, v49
	v_exp_f32_e32 v46, v46
	v_exp_f32_e32 v47, v47
	v_exp_f32_e32 v48, v44
	v_exp_f32_e32 v49, v45
	v_add_f32_e32 v44, 1.0, v46
	v_add_f32_e32 v45, 1.0, v47
	v_add_f32_e32 v46, 1.0, v48
	v_add_f32_e32 v47, 1.0, v49
	v_rcp_f32_e32 v44, v44
	v_rcp_f32_e32 v45, v45
	v_rcp_f32_e32 v46, v46
	v_rcp_f32_e32 v47, v47
	v_mul_f32_e32 v50, v251, v251
	v_pk_mul_f32 v[32:33], v[32:33], v[50:51] op_sel_hi:[1,0]
	v_pk_mul_f32 v[34:35], v[34:35], v[50:51] op_sel_hi:[1,0]
	v_pk_mul_f32 v[40:41], v[40:41], v[50:51] op_sel_hi:[1,0]
	v_pk_mul_f32 v[42:43], v[42:43], v[50:51] op_sel_hi:[1,0]
	v_pk_mul_f32 v[36:37], v[34:35], v[46:47]
	v_pk_mul_f32 v[34:35], v[32:33], v[44:45]
	v_add_u32_e32 v38, 0x90, v181
	v_pk_mul_f32 v[42:43], v[42:43], v[54:55]
	v_pk_mul_f32 v[40:41], v[40:41], v[52:53]
	s_nop 0
	v_cvt_pk_bf16_f32 v32, v40, v41
	v_cvt_pk_bf16_f32 v33, v42, v43
	v_cvt_pk_bf16_f32 v34, v34, v35
	v_cvt_pk_bf16_f32 v35, v36, v37
	v_mad_i64_i32 v[36:37], s[0:1], v38, s44, v[112:113]
	v_lshl_add_u64 v[36:37], v[36:37], 0, v[114:115]
	global_store_dwordx4 v[36:37], v[32:35], off
	s_nop 1
	v_mul_f32_e32 v32, 0xbfb8aa3b, v243
	v_pk_mul_f32 v[38:39], v[28:29], v[32:33] op_sel_hi:[1,0]
	v_pk_mul_f32 v[36:37], v[30:31], v[32:33] op_sel_hi:[1,0]
	v_exp_f32_e32 v33, v38
	v_exp_f32_e32 v35, v39
	v_exp_f32_e32 v38, v36
	v_exp_f32_e32 v39, v37
	v_add_f32_e32 v33, 1.0, v33
	v_rcp_f32_e32 v36, v33
	v_add_f32_e32 v33, 1.0, v35
	v_rcp_f32_e32 v37, v33
	v_add_f32_e32 v33, 1.0, v38
	v_rcp_f32_e32 v38, v33
	v_add_f32_e32 v33, 1.0, v39
	v_pk_mul_f32 v[28:29], v[22:23], v[32:33] op_sel_hi:[1,0]
	v_pk_mul_f32 v[30:31], v[20:21], v[32:33] op_sel_hi:[1,0]
	v_rcp_f32_e32 v39, v33
	v_exp_f32_e32 v30, v30
	v_exp_f32_e32 v31, v31
	v_exp_f32_e32 v32, v28
	v_exp_f32_e32 v33, v29
	v_add_f32_e32 v28, 1.0, v30
	v_add_f32_e32 v29, 1.0, v31
	v_add_f32_e32 v30, 1.0, v32
	v_add_f32_e32 v31, 1.0, v33
	v_rcp_f32_e32 v28, v28
	v_rcp_f32_e32 v29, v29
	v_rcp_f32_e32 v30, v30
	v_rcp_f32_e32 v31, v31
	v_mul_f32_e32 v34, v243, v243
	v_pk_mul_f32 v[16:17], v[16:17], v[34:35] op_sel_hi:[1,0]
	v_pk_mul_f32 v[18:19], v[18:19], v[34:35] op_sel_hi:[1,0]
	v_pk_mul_f32 v[24:25], v[24:25], v[34:35] op_sel_hi:[1,0]
	v_pk_mul_f32 v[26:27], v[26:27], v[34:35] op_sel_hi:[1,0]
	v_pk_mul_f32 v[20:21], v[18:19], v[30:31]
	v_pk_mul_f32 v[18:19], v[16:17], v[28:29]
	v_add_u32_e32 v22, 0xa0, v181
	v_pk_mul_f32 v[26:27], v[26:27], v[38:39]
	v_pk_mul_f32 v[24:25], v[24:25], v[36:37]
	s_nop 0
	v_cvt_pk_bf16_f32 v16, v24, v25
	v_cvt_pk_bf16_f32 v17, v26, v27
	v_cvt_pk_bf16_f32 v18, v18, v19
	v_cvt_pk_bf16_f32 v19, v20, v21
	v_mad_i64_i32 v[20:21], s[0:1], v22, s44, v[112:113]
	v_lshl_add_u64 v[20:21], v[20:21], 0, v[114:115]
	global_store_dwordx4 v[20:21], v[16:19], off
	s_nop 1
	v_mul_f32_e32 v16, 0xbfb8aa3b, v248
	v_pk_mul_f32 v[22:23], v[12:13], v[16:17] op_sel_hi:[1,0]
	v_pk_mul_f32 v[20:21], v[14:15], v[16:17] op_sel_hi:[1,0]
	v_exp_f32_e32 v17, v22
	v_exp_f32_e32 v19, v23
	v_exp_f32_e32 v22, v20
	v_exp_f32_e32 v23, v21
	v_add_f32_e32 v17, 1.0, v17
	v_rcp_f32_e32 v20, v17
	v_add_f32_e32 v17, 1.0, v19
	v_rcp_f32_e32 v21, v17
	v_add_f32_e32 v17, 1.0, v22
	v_rcp_f32_e32 v22, v17
	v_add_f32_e32 v17, 1.0, v23
	v_pk_mul_f32 v[12:13], v[6:7], v[16:17] op_sel_hi:[1,0]
	v_pk_mul_f32 v[14:15], v[4:5], v[16:17] op_sel_hi:[1,0]
	v_rcp_f32_e32 v23, v17
	v_exp_f32_e32 v14, v14
	v_exp_f32_e32 v15, v15
	v_exp_f32_e32 v16, v12
	v_exp_f32_e32 v17, v13
	v_add_f32_e32 v12, 1.0, v14
	v_add_f32_e32 v13, 1.0, v15
	v_add_f32_e32 v14, 1.0, v16
	v_add_f32_e32 v15, 1.0, v17
	v_rcp_f32_e32 v12, v12
	v_rcp_f32_e32 v13, v13
	v_rcp_f32_e32 v14, v14
	v_rcp_f32_e32 v15, v15
	v_mul_f32_e32 v18, v248, v248
	v_pk_mul_f32 v[0:1], v[0:1], v[18:19] op_sel_hi:[1,0]
	v_pk_mul_f32 v[2:3], v[2:3], v[18:19] op_sel_hi:[1,0]
	v_pk_mul_f32 v[8:9], v[8:9], v[18:19] op_sel_hi:[1,0]
	v_pk_mul_f32 v[10:11], v[10:11], v[18:19] op_sel_hi:[1,0]
	v_pk_mul_f32 v[4:5], v[2:3], v[14:15]
	v_pk_mul_f32 v[2:3], v[0:1], v[12:13]
	v_add_u32_e32 v6, 0xb0, v181
	v_pk_mul_f32 v[10:11], v[10:11], v[22:23]
	v_pk_mul_f32 v[8:9], v[8:9], v[20:21]
	s_nop 0
	v_cvt_pk_bf16_f32 v0, v8, v9
	v_cvt_pk_bf16_f32 v1, v10, v11
	v_cvt_pk_bf16_f32 v2, v2, v3
	v_cvt_pk_bf16_f32 v3, v4, v5
	v_mad_i64_i32 v[4:5], s[0:1], v6, s44, v[112:113]
	v_lshl_add_u64 v[4:5], v[4:5], 0, v[114:115]
	s_mov_b64 s[0:1], -1
	global_store_dwordx4 v[4:5], v[0:3], off
	s_cbranch_vccnz .LBB0_1360
	s_andn2_b64 vcc, exec, s[8:9]
	s_cbranch_vccnz .LBB0_1359
	s_barrier
	s_branch .LBB0_1359
